# v15 + EpiRes epilogues (w_out / ffn_out GEMMs): LN gamma/beta tile staged once per unit in LDS; the 16 in-loop global loads+vmcnt(0) per unit become ds_read_b128
# speedup vs baseline: 1.0283x; 1.0071x over previous
; __device__ __forceinline__ void ln_table(const float* st, int pm, int key, int wr, int wc, int fr, int fq) {
;     ...
;     if (st) {
;         const int want = key * 128 + pm + 1;
;         if (__builtin_amdgcn_readfirstlane(*kw) != want) {
;             if (t < 256) {
;                 const f32x4* p = (const f32x4*)(st + ((size_t)(pm * 256 + t)) * 32);
;                 float s = 0.f, q = 0.f;
; #pragma unroll
;                 for (int i = 0; i < 8; ++i) { const f32x4 v = p[i]; s += v[0] + v[2]; q += v[1] + v[3]; }
;                 const float mu = s * (1.f / D);
;                 tab[t] = (f32x2v){mu, __builtin_amdgcn_rsqf(fmaxf(q * (1.f / D) - mu * mu, 0.f) + LN_EPS)};
;     __device__ __forceinline__ void operator()(const pg8::f32x4 (&acc)[2][2][4][2], const pg8::Unit& u, int wr, int wc, int fr, int fq) const {
;     ...
;                 for (int bj = 0; bj < 2; ++bj) zx[m][bj] = *(const u32x4*)(ZB + (size_t)(u.pm * 256 + ai * 128 + wr * 64 + m * 16 + fr) * 1024 + col0 + bj * 128);
;             if (ai == 0) ln_table(pst, u.pm, key, wr, wc, fr, fq);
.LBB0_1435:
	v_mov_b32_e32 v196, v209
	v_mov_b32_e32 v213, v208
	s_lshl_b32 s0, s4, 8
	s_or_b32 s0, s0, s19
	s_lshl_b32 s42, s8, 8
	v_add_u32_e32 v212, s18, v196
	v_lshl_add_u32 v172, v213, 3, s0
	v_and_b32_e32 v186, 0xffffff00, v172
	v_and_b32_e32 v187, 0xff, v216
	v_add_lshl_u32 v186, v186, v187, 2
	v_mov_b32_e32 v187, 0
	v_cmp_gt_u32_e32 vcc, 0x100, v216
	v_mov_b32_e32 v188, s50
	v_mov_b32_e32 v189, s51
	s_and_saveexec_b64 vcc, vcc
	v_mov_b32_e32 v188, s48
	v_mov_b32_e32 v189, s49
	s_mov_b64 exec, vcc
	v_lshl_add_u64 v[188:189], v[188:189], 0, v[186:187]
	global_load_dword v186, v[188:189], off
	v_lshlrev_b32_e32 v187, 2, v216
	v_add_u32_e32 v187, 0x21000, v187
	v_and_b32_e32 v80, 0xff, v172
	v_lshlrev_b32_e32 v80, 2, v80
	v_add_u32_e32 v80, 0x21000, v80
	v_add_u32_e32 v176, s42, v212
	v_ashrrev_i32_e32 v173, 31, v172
	v_ashrrev_i32_e32 v177, 31, v176
	v_add_u32_e32 v190, 16, v176
	v_lshl_add_u64 v[174:175], v[172:173], 1, s[20:21]
	v_lshlrev_b64 v[194:195], 11, v[176:177]
	v_ashrrev_i32_e32 v191, 31, v190
	v_add_u32_e32 v182, 32, v176
	v_lshl_add_u64 v[114:115], v[174:175], 0, v[194:195]
	v_lshlrev_b64 v[192:193], 11, v[190:191]
	v_ashrrev_i32_e32 v183, 31, v182
	v_add_u32_e32 v178, 48, v176
	global_load_dwordx4 v[158:161], v[114:115], off
	global_load_dwordx4 v[154:157], v[114:115], off offset:256
	v_lshl_add_u64 v[114:115], v[174:175], 0, v[192:193]
	v_lshlrev_b64 v[184:185], 11, v[182:183]
	v_ashrrev_i32_e32 v179, 31, v178
	global_load_dwordx4 v[150:153], v[114:115], off
	global_load_dwordx4 v[146:149], v[114:115], off offset:256
	v_lshl_add_u64 v[114:115], v[174:175], 0, v[184:185]
	v_lshlrev_b64 v[180:181], 11, v[178:179]
	global_load_dwordx4 v[142:145], v[114:115], off
	global_load_dwordx4 v[138:141], v[114:115], off offset:256
	v_lshl_add_u64 v[114:115], v[174:175], 0, v[180:181]
	global_load_dwordx4 v[118:121], v[114:115], off
	s_nop 0
	global_load_dwordx4 v[114:117], v[114:115], off offset:256
	s_waitcnt vmcnt(8)
	ds_write_b32 v187, v186
	v_cndmask_b32_e64 v186, 0, 1, s[56:57]
	v_cmp_ne_u32_e64 s[40:41], 1, v186
	s_andn2_b64 vcc, exec, s[56:57]
	s_cbranch_vccnz .LBB0_1443
	ds_read_b32 v186, v223
	s_add_i32 s5, s75, s8
	s_waitcnt lgkmcnt(0)
	v_readfirstlane_b32 s0, v186
	s_cmp_eq_u32 s0, s5
	s_cbranch_scc1 .LBB0_1442
	v_lshlrev_b32_e32 v186, 4, v213
	v_add3_u32 v196, s71, v196, v186
	s_movk_i32 s0, 0x100
	v_cmp_gt_i32_e32 vcc, s0, v196
	s_and_saveexec_b64 s[0:1], vcc
	s_cbranch_execz .LBB0_1439
	v_add_u32_e32 v186, s42, v196
	v_ashrrev_i32_e32 v187, 31, v186
	v_lshlrev_b64 v[186:187], 7, v[186:187]
	v_lshl_add_u64 v[186:187], s[46:47], 0, v[186:187]
	global_load_dwordx4 v[198:201], v[186:187], off
	global_load_dwordx4 v[202:205], v[186:187], off offset:16
	global_load_dwordx4 v[234:237], v[186:187], off offset:32
	global_load_dwordx4 v[238:241], v[186:187], off offset:48
	global_load_dwordx4 v[242:245], v[186:187], off offset:64
	global_load_dwordx4 v[246:249], v[186:187], off offset:80
	global_load_dwordx4 v[226:229], v[186:187], off offset:96
	s_nop 0
	global_load_dwordx4 v[186:189], v[186:187], off offset:112
	s_mov_b32 s8, 0x3a800000
	s_waitcnt vmcnt(0)
	v_pk_add_f32 v[198:199], v[198:199], v[200:201]
	v_pk_add_f32 v[200:201], v[202:203], v[204:205]
	v_pk_add_f32 v[198:199], v[198:199], 0 op_sel_hi:[1,0]
	v_pk_add_f32 v[202:203], v[234:235], v[236:237]
	v_pk_add_f32 v[198:199], v[198:199], v[200:201]
	v_pk_add_f32 v[204:205], v[238:239], v[240:241]
	v_pk_add_f32 v[198:199], v[198:199], v[202:203]
	v_pk_add_f32 v[206:207], v[242:243], v[244:245]
	v_pk_add_f32 v[198:199], v[198:199], v[204:205]
	v_pk_add_f32 v[214:215], v[246:247], v[248:249]
	v_pk_add_f32 v[198:199], v[198:199], v[206:207]
	v_pk_add_f32 v[226:227], v[226:227], v[228:229]
	v_pk_add_f32 v[198:199], v[198:199], v[214:215]
	v_pk_add_f32 v[186:187], v[186:187], v[188:189]
	v_pk_add_f32 v[198:199], v[198:199], v[226:227]
	v_lshl_add_u32 v188, v196, 3, v225
	v_pk_add_f32 v[186:187], v[198:199], v[186:187]
	s_nop 0
	v_pk_mul_f32 v[186:187], v[186:187], s[8:9] op_sel_hi:[1,0]
	s_nop 0
	v_fma_f32 v187, -v186, v186, v187
	v_max_f32_e32 v187, 0, v187
	v_add_f32_e32 v187, 0x3727c5ac, v187
	v_rsq_f32_e32 v187, v187
	ds_write_b64 v188, v[186:187]

; __device__ __forceinline__ float bflo(unsigned w) { return __uint_as_float(w << 16); }
; __device__ __forceinline__ float bfhi(unsigned w) { return __uint_as_float(w & 0xffff0000u); }
; __device__ __forceinline__ u32x4 pack8(f32x4 a, f32x4 b) { u32x4 w; w.x = cvtpk(a[0], a[1]); w.y = cvtpk(a[2], a[3]); w.z = cvtpk(b[0], b[1]); w.w = cvtpk(b[2], b[3]); return w; }
;     __device__ __forceinline__ void operator()(const pg8::f32x4 (&acc)[2][2][4][2], const pg8::Unit& u, int wr, int wc, int fr, int fq) const {
;     ...
;             for (int m = 0; m < 4; ++m) {
;                 const int rloc = ai * 128 + wr * 64 + m * 16 + fr, row = u.pm * 256 + rloc;
;                 float mu = 0.f, rstd = 1.f; if (pst) ln_row_stats(pst, rloc, mu, rstd);
;                 float s = 0.f, q = 0.f;
; #pragma unroll
;                 for (int bj = 0; bj < 2; ++bj) {
;                     const int col = col0 + bj * 128;
;                     const u32x4 zw = zx[m][bj];
;                     f32x4 x0 = {bflo(zw.x), bfhi(zw.x), bflo(zw.y), bfhi(zw.y)}, x1 = {bflo(zw.z), bfhi(zw.z), bflo(zw.w), bfhi(zw.w)};
;                     if (pst) { const f32x4 g0 = *(const f32x4*)(pg + col), g1 = *(const f32x4*)(pg + col + 4), b0 = *(const f32x4*)(pb + col), b1 = *(const f32x4*)(pb + col + 4);
;                         x0 = (x0 - mu) * rstd * g0 + b0; x1 = (x1 - mu) * rstd * g1 + b1; }
;                     x0 = x0 * ALPHA + acc[ai][bj][m][0]; x1 = x1 * ALPHA + acc[ai][bj][m][1];
;                     if (Z) { float* p = Z + (size_t)row * 1024 + col; *(f32x4*)p = x0; *(f32x4*)(p + 4) = x1; }
;                     *(u32x4*)(ZB + (size_t)row * 1024 + col) = pack8(x0, x1);
.LBB0_1444:
	s_waitcnt vmcnt(0)
	s_waitcnt lgkmcnt(0)
	s_barrier
	v_lshlrev_b32_e32 v202, 16, v160
	v_and_b32_e32 v203, 0xffff0000, v160
	v_lshlrev_b32_e32 v204, 16, v161
	v_and_b32_e32 v205, 0xffff0000, v161
	v_lshlrev_b64 v[160:161], 2, v[172:173]
	v_mov_b32_e32 v197, v196
	v_lshlrev_b32_e32 v206, 16, v158
	v_and_b32_e32 v207, 0xffff0000, v158
	v_lshlrev_b32_e32 v200, 16, v159
	v_and_b32_e32 v201, 0xffff0000, v159
	s_and_b64 vcc, exec, s[40:41]
	v_lshl_add_u64 v[158:159], s[48:49], 0, v[160:161]
	v_lshl_add_u64 v[160:161], s[50:51], 0, v[160:161]
	s_cbranch_vccnz .LBB0_1446
	ds_read_b128 v[186:189], v80 offset:1024
	ds_read_b128 v[226:229], v80
	ds_read_b128 v[234:237], v80 offset:16
	ds_read_b128 v[238:241], v80 offset:1040
	v_sub_f32_e32 v201, v201, v198
	v_sub_f32_e32 v200, v200, v198
	v_sub_f32_e32 v207, v207, v198
	v_sub_f32_e32 v206, v206, v198
	v_mov_b32_e32 v214, v196
	v_mov_b32_e32 v215, v196
	v_sub_f32_e32 v205, v205, v198
	v_sub_f32_e32 v204, v204, v198
	v_sub_f32_e32 v203, v203, v198
	v_sub_f32_e32 v202, v202, v198
	v_pk_mul_f32 v[206:207], v[196:197], v[206:207]
	v_pk_mul_f32 v[200:201], v[214:215], v[200:201]
	v_pk_mul_f32 v[202:203], v[196:197], v[202:203]
	v_pk_mul_f32 v[204:205], v[214:215], v[204:205]
	s_waitcnt lgkmcnt(0)
	v_pk_fma_f32 v[200:201], v[200:201], v[228:229], v[188:189]
	v_pk_fma_f32 v[206:207], v[206:207], v[226:227], v[186:187]
	s_nop 0
	v_pk_fma_f32 v[204:205], v[204:205], v[236:237], v[240:241]
	v_pk_fma_f32 v[202:203], v[202:203], v[234:235], v[238:239]
.LBB0_1446:
	v_pk_fma_f32 v[200:201], v[200:201], s[34:35], v[136:137] op_sel_hi:[1,0,1]
	v_pk_fma_f32 v[136:137], v[206:207], s[34:35], v[134:135] op_sel_hi:[1,0,1]
	v_pk_fma_f32 v[132:133], v[204:205], s[34:35], v[132:133] op_sel_hi:[1,0,1]
	v_pk_fma_f32 v[134:135], v[202:203], s[34:35], v[130:131] op_sel_hi:[1,0,1]
	v_lshl_add_u64 v[130:131], s[20:21], 0, v[194:195]
	v_cvt_pk_bf16_f32 v186, v136, v137
	v_cvt_pk_bf16_f32 v187, v200, v201
	v_cvt_pk_bf16_f32 v188, v134, v135
	v_cvt_pk_bf16_f32 v189, v132, v133
	v_lshl_add_u64 v[130:131], v[172:173], 1, v[130:131]
	v_lshlrev_b32_e32 v194, 16, v154
	v_and_b32_e32 v195, 0xffff0000, v154
	v_lshlrev_b32_e32 v202, 16, v155
	v_and_b32_e32 v203, 0xffff0000, v155
	v_lshlrev_b32_e32 v154, 16, v156
	v_and_b32_e32 v155, 0xffff0000, v156
	v_lshlrev_b32_e32 v156, 16, v157
	s_and_b64 vcc, exec, s[40:41]
	v_and_b32_e32 v157, 0xffff0000, v157
	global_store_dwordx4 v[130:131], v[186:189], off
	s_cbranch_vccnz .LBB0_1448
	ds_read_b128 v[186:189], v80 offset:1536
	ds_read_b128 v[204:207], v80 offset:512
	ds_read_b128 v[226:229], v80 offset:528
	ds_read_b128 v[234:237], v80 offset:1552
	v_sub_f32_e32 v203, v203, v198
	v_sub_f32_e32 v202, v202, v198
	v_sub_f32_e32 v195, v195, v198
	v_sub_f32_e32 v194, v194, v198
	v_mov_b32_e32 v214, v196
	v_mov_b32_e32 v215, v196
	v_sub_f32_e32 v157, v157, v198
	v_sub_f32_e32 v156, v156, v198
	v_sub_f32_e32 v155, v155, v198
	v_sub_f32_e32 v154, v154, v198
	v_pk_mul_f32 v[194:195], v[196:197], v[194:195]
	v_pk_mul_f32 v[198:199], v[214:215], v[202:203]
	v_pk_mul_f32 v[154:155], v[196:197], v[154:155]
	v_pk_mul_f32 v[156:157], v[214:215], v[156:157]
	s_waitcnt lgkmcnt(0)
	v_pk_fma_f32 v[202:203], v[198:199], v[206:207], v[188:189]
	v_pk_fma_f32 v[194:195], v[194:195], v[204:205], v[186:187]
	s_nop 0
	v_pk_fma_f32 v[156:157], v[156:157], v[228:229], v[236:237]
	v_pk_fma_f32 v[154:155], v[154:155], v[226:227], v[234:235]

; __device__ __forceinline__ float bflo(unsigned w) { return __uint_as_float(w << 16); }
; __device__ __forceinline__ float bfhi(unsigned w) { return __uint_as_float(w & 0xffff0000u); }
; __device__ __forceinline__ u32x4 pack8(f32x4 a, f32x4 b) { u32x4 w; w.x = cvtpk(a[0], a[1]); w.y = cvtpk(a[2], a[3]); w.z = cvtpk(b[0], b[1]); w.w = cvtpk(b[2], b[3]); return w; }
;     __device__ __forceinline__ void operator()(const pg8::f32x4 (&acc)[2][2][4][2], const pg8::Unit& u, int wr, int wc, int fr, int fq) const {
;     ...
;             for (int m = 0; m < 4; ++m) {
;                 const int rloc = ai * 128 + wr * 64 + m * 16 + fr, row = u.pm * 256 + rloc;
;                 float mu = 0.f, rstd = 1.f; if (pst) ln_row_stats(pst, rloc, mu, rstd);
;                 float s = 0.f, q = 0.f;
; #pragma unroll
;                 for (int bj = 0; bj < 2; ++bj) {
;                     const int col = col0 + bj * 128;
;                     const u32x4 zw = zx[m][bj];
;                     f32x4 x0 = {bflo(zw.x), bfhi(zw.x), bflo(zw.y), bfhi(zw.y)}, x1 = {bflo(zw.z), bfhi(zw.z), bflo(zw.w), bfhi(zw.w)};
;                     if (pst) { const f32x4 g0 = *(const f32x4*)(pg + col), g1 = *(const f32x4*)(pg + col + 4), b0 = *(const f32x4*)(pb + col), b1 = *(const f32x4*)(pb + col + 4);
;                         x0 = (x0 - mu) * rstd * g0 + b0; x1 = (x1 - mu) * rstd * g1 + b1; }
;                     x0 = x0 * ALPHA + acc[ai][bj][m][0]; x1 = x1 * ALPHA + acc[ai][bj][m][1];
;                     if (Z) { float* p = Z + (size_t)row * 1024 + col; *(f32x4*)p = x0; *(f32x4*)(p + 4) = x1; }
;                     *(u32x4*)(ZB + (size_t)row * 1024 + col) = pack8(x0, x1);
.LBB0_1453:
	v_mov_b32_e32 v123, v122
	v_lshlrev_b32_e32 v132, 16, v150
	v_and_b32_e32 v133, 0xffff0000, v150
	v_lshlrev_b32_e32 v126, 16, v151
	v_and_b32_e32 v127, 0xffff0000, v151
	v_lshlrev_b32_e32 v128, 16, v152
	v_and_b32_e32 v129, 0xffff0000, v152
	v_lshlrev_b32_e32 v130, 16, v153
	s_and_b64 vcc, exec, s[40:41]
	v_and_b32_e32 v131, 0xffff0000, v153
	s_cbranch_vccnz .LBB0_1455
	ds_read_b128 v[134:137], v80 offset:1024
	ds_read_b128 v[150:153], v80
	ds_read_b128 v[154:157], v80 offset:16
	ds_read_b128 v[186:189], v80 offset:1040
	v_sub_f32_e32 v127, v127, v124
	v_sub_f32_e32 v126, v126, v124
	v_sub_f32_e32 v133, v133, v124
	v_sub_f32_e32 v132, v132, v124
	v_mov_b32_e32 v194, v122
	v_mov_b32_e32 v195, v122
	v_sub_f32_e32 v131, v131, v124
	v_sub_f32_e32 v130, v130, v124
	v_sub_f32_e32 v129, v129, v124
	v_sub_f32_e32 v128, v128, v124
	v_pk_mul_f32 v[132:133], v[122:123], v[132:133]
	v_pk_mul_f32 v[126:127], v[194:195], v[126:127]
	v_pk_mul_f32 v[128:129], v[122:123], v[128:129]
	v_pk_mul_f32 v[130:131], v[194:195], v[130:131]
	s_waitcnt lgkmcnt(0)
	v_pk_fma_f32 v[126:127], v[126:127], v[152:153], v[136:137]
	v_pk_fma_f32 v[132:133], v[132:133], v[150:151], v[134:135]
	s_nop 0
	v_pk_fma_f32 v[130:131], v[130:131], v[156:157], v[188:189]
	v_pk_fma_f32 v[128:129], v[128:129], v[154:155], v[186:187]
.LBB0_1455:
	v_pk_fma_f32 v[126:127], v[126:127], s[34:35], v[112:113] op_sel_hi:[1,0,1]
	v_pk_fma_f32 v[112:113], v[132:133], s[34:35], v[110:111] op_sel_hi:[1,0,1]
	v_pk_fma_f32 v[108:109], v[130:131], s[34:35], v[108:109] op_sel_hi:[1,0,1]
	v_pk_fma_f32 v[110:111], v[128:129], s[34:35], v[106:107] op_sel_hi:[1,0,1]
	v_lshl_add_u64 v[106:107], s[20:21], 0, v[192:193]
	v_cvt_pk_bf16_f32 v128, v112, v113
	v_cvt_pk_bf16_f32 v129, v126, v127
	v_cvt_pk_bf16_f32 v130, v110, v111
	v_cvt_pk_bf16_f32 v131, v108, v109
	v_lshl_add_u64 v[106:107], v[172:173], 1, v[106:107]
	global_store_dwordx4 v[106:107], v[128:131], off
	v_lshlrev_b32_e32 v132, 16, v146
	v_and_b32_e32 v133, 0xffff0000, v146
	v_lshlrev_b32_e32 v134, 16, v147
	v_and_b32_e32 v135, 0xffff0000, v147
	v_lshlrev_b32_e32 v128, 16, v148
	v_and_b32_e32 v129, 0xffff0000, v148
	v_lshlrev_b32_e32 v130, 16, v149
	s_and_b64 vcc, exec, s[40:41]
	v_and_b32_e32 v131, 0xffff0000, v149
	s_cbranch_vccnz .LBB0_1457
	ds_read_b128 v[146:149], v80 offset:1536
	ds_read_b128 v[150:153], v80 offset:512
	ds_read_b128 v[154:157], v80 offset:528
	ds_read_b128 v[186:189], v80 offset:1552
	v_sub_f32_e32 v135, v135, v124
	v_sub_f32_e32 v134, v134, v124
	v_sub_f32_e32 v133, v133, v124
	v_sub_f32_e32 v132, v132, v124
	v_mov_b32_e32 v136, v122
	v_mov_b32_e32 v137, v122
	v_sub_f32_e32 v131, v131, v124
	v_sub_f32_e32 v130, v130, v124
	s_waitcnt lgkmcnt(0)
	v_sub_f32_e32 v125, v129, v124
	v_sub_f32_e32 v124, v128, v124
	v_pk_mul_f32 v[128:129], v[122:123], v[132:133]
	v_pk_mul_f32 v[132:133], v[136:137], v[134:135]
	v_pk_mul_f32 v[122:123], v[122:123], v[124:125]
	v_pk_mul_f32 v[124:125], v[136:137], v[130:131]
	s_nop 0
	v_pk_fma_f32 v[134:135], v[132:133], v[152:153], v[148:149]
	v_pk_fma_f32 v[132:133], v[128:129], v[150:151], v[146:147]
	s_nop 0
	v_pk_fma_f32 v[130:131], v[124:125], v[156:157], v[188:189]
	v_pk_fma_f32 v[128:129], v[122:123], v[154:155], v[186:187]

; __device__ __forceinline__ float bflo(unsigned w) { return __uint_as_float(w << 16); }
; __device__ __forceinline__ float bfhi(unsigned w) { return __uint_as_float(w & 0xffff0000u); }
; __device__ __forceinline__ u32x4 pack8(f32x4 a, f32x4 b) { u32x4 w; w.x = cvtpk(a[0], a[1]); w.y = cvtpk(a[2], a[3]); w.z = cvtpk(b[0], b[1]); w.w = cvtpk(b[2], b[3]); return w; }
;     __device__ __forceinline__ void operator()(const pg8::f32x4 (&acc)[2][2][4][2], const pg8::Unit& u, int wr, int wc, int fr, int fq) const {
;     ...
;             for (int m = 0; m < 4; ++m) {
;                 const int rloc = ai * 128 + wr * 64 + m * 16 + fr, row = u.pm * 256 + rloc;
;                 float mu = 0.f, rstd = 1.f; if (pst) ln_row_stats(pst, rloc, mu, rstd);
;                 float s = 0.f, q = 0.f;
; #pragma unroll
;                 for (int bj = 0; bj < 2; ++bj) {
;                     const int col = col0 + bj * 128;
;                     const u32x4 zw = zx[m][bj];
;                     f32x4 x0 = {bflo(zw.x), bfhi(zw.x), bflo(zw.y), bfhi(zw.y)}, x1 = {bflo(zw.z), bfhi(zw.z), bflo(zw.w), bfhi(zw.w)};
;                     if (pst) { const f32x4 g0 = *(const f32x4*)(pg + col), g1 = *(const f32x4*)(pg + col + 4), b0 = *(const f32x4*)(pb + col), b1 = *(const f32x4*)(pb + col + 4);
;                         x0 = (x0 - mu) * rstd * g0 + b0; x1 = (x1 - mu) * rstd * g1 + b1; }
;                     x0 = x0 * ALPHA + acc[ai][bj][m][0]; x1 = x1 * ALPHA + acc[ai][bj][m][1];
;                     if (Z) { float* p = Z + (size_t)row * 1024 + col; *(f32x4*)p = x0; *(f32x4*)(p + 4) = x1; }
;                     *(u32x4*)(ZB + (size_t)row * 1024 + col) = pack8(x0, x1);
.LBB0_1462:
	v_mov_b32_e32 v99, v98
	v_lshlrev_b32_e32 v108, 16, v142
	v_and_b32_e32 v109, 0xffff0000, v142
	v_lshlrev_b32_e32 v102, 16, v143
	v_and_b32_e32 v103, 0xffff0000, v143
	v_lshlrev_b32_e32 v104, 16, v144
	v_and_b32_e32 v105, 0xffff0000, v144
	v_lshlrev_b32_e32 v106, 16, v145
	s_and_b64 vcc, exec, s[40:41]
	v_and_b32_e32 v107, 0xffff0000, v145
	s_cbranch_vccnz .LBB0_1464
	ds_read_b128 v[110:113], v80 offset:1024
	ds_read_b128 v[122:125], v80
	ds_read_b128 v[126:129], v80 offset:16
	ds_read_b128 v[130:133], v80 offset:1040
	v_sub_f32_e32 v103, v103, v100
	v_sub_f32_e32 v102, v102, v100
	v_sub_f32_e32 v109, v109, v100
	v_sub_f32_e32 v108, v108, v100
	v_mov_b32_e32 v134, v98
	v_mov_b32_e32 v135, v98
	v_sub_f32_e32 v107, v107, v100
	v_sub_f32_e32 v106, v106, v100
	v_sub_f32_e32 v105, v105, v100
	v_sub_f32_e32 v104, v104, v100
	v_pk_mul_f32 v[108:109], v[98:99], v[108:109]
	v_pk_mul_f32 v[102:103], v[134:135], v[102:103]
	v_pk_mul_f32 v[104:105], v[98:99], v[104:105]
	v_pk_mul_f32 v[106:107], v[134:135], v[106:107]
	s_waitcnt lgkmcnt(0)
	v_pk_fma_f32 v[102:103], v[102:103], v[124:125], v[112:113]
	v_pk_fma_f32 v[108:109], v[108:109], v[122:123], v[110:111]
	s_nop 0
	v_pk_fma_f32 v[106:107], v[106:107], v[128:129], v[132:133]
	v_pk_fma_f32 v[104:105], v[104:105], v[126:127], v[130:131]
.LBB0_1464:
	v_pk_fma_f32 v[102:103], v[102:103], s[34:35], v[96:97] op_sel_hi:[1,0,1]
	v_pk_fma_f32 v[96:97], v[108:109], s[34:35], v[94:95] op_sel_hi:[1,0,1]
	v_pk_fma_f32 v[92:93], v[106:107], s[34:35], v[92:93] op_sel_hi:[1,0,1]
	v_pk_fma_f32 v[94:95], v[104:105], s[34:35], v[90:91] op_sel_hi:[1,0,1]
	v_lshl_add_u64 v[90:91], s[20:21], 0, v[184:185]
	v_cvt_pk_bf16_f32 v104, v96, v97
	v_cvt_pk_bf16_f32 v105, v102, v103
	v_cvt_pk_bf16_f32 v106, v94, v95
	v_cvt_pk_bf16_f32 v107, v92, v93
	v_lshl_add_u64 v[90:91], v[172:173], 1, v[90:91]
	global_store_dwordx4 v[90:91], v[104:107], off
	v_lshlrev_b32_e32 v108, 16, v138
	v_and_b32_e32 v109, 0xffff0000, v138
	v_lshlrev_b32_e32 v110, 16, v139
	v_and_b32_e32 v111, 0xffff0000, v139
	v_lshlrev_b32_e32 v104, 16, v140
	v_and_b32_e32 v105, 0xffff0000, v140
	v_lshlrev_b32_e32 v106, 16, v141
	s_and_b64 vcc, exec, s[40:41]
	v_and_b32_e32 v107, 0xffff0000, v141
	s_cbranch_vccnz .LBB0_1466
	ds_read_b128 v[122:125], v80 offset:1536
	ds_read_b128 v[126:129], v80 offset:512
	ds_read_b128 v[130:133], v80 offset:528
	ds_read_b128 v[134:137], v80 offset:1552
	v_sub_f32_e32 v111, v111, v100
	v_sub_f32_e32 v110, v110, v100
	v_sub_f32_e32 v109, v109, v100
	v_sub_f32_e32 v108, v108, v100
	v_mov_b32_e32 v112, v98
	v_mov_b32_e32 v113, v98
	v_sub_f32_e32 v107, v107, v100
	v_sub_f32_e32 v106, v106, v100
	s_waitcnt lgkmcnt(0)
	v_sub_f32_e32 v101, v105, v100
	v_sub_f32_e32 v100, v104, v100
	v_pk_mul_f32 v[104:105], v[98:99], v[108:109]
	v_pk_mul_f32 v[108:109], v[112:113], v[110:111]
	v_pk_mul_f32 v[98:99], v[98:99], v[100:101]
	v_pk_mul_f32 v[100:101], v[112:113], v[106:107]
	s_nop 0
	v_pk_fma_f32 v[110:111], v[108:109], v[128:129], v[124:125]
	v_pk_fma_f32 v[108:109], v[104:105], v[126:127], v[122:123]
	s_nop 0
	v_pk_fma_f32 v[106:107], v[100:101], v[132:133], v[136:137]
	v_pk_fma_f32 v[104:105], v[98:99], v[130:131], v[134:135]

; __device__ __forceinline__ float bflo(unsigned w) { return __uint_as_float(w << 16); }
; __device__ __forceinline__ float bfhi(unsigned w) { return __uint_as_float(w & 0xffff0000u); }
; __device__ __forceinline__ u32x4 pack8(f32x4 a, f32x4 b) { u32x4 w; w.x = cvtpk(a[0], a[1]); w.y = cvtpk(a[2], a[3]); w.z = cvtpk(b[0], b[1]); w.w = cvtpk(b[2], b[3]); return w; }
;     __device__ __forceinline__ void operator()(const pg8::f32x4 (&acc)[2][2][4][2], const pg8::Unit& u, int wr, int wc, int fr, int fq) const {
;     ...
;             for (int m = 0; m < 4; ++m) {
;                 const int rloc = ai * 128 + wr * 64 + m * 16 + fr, row = u.pm * 256 + rloc;
;                 float mu = 0.f, rstd = 1.f; if (pst) ln_row_stats(pst, rloc, mu, rstd);
;                 float s = 0.f, q = 0.f;
; #pragma unroll
;                 for (int bj = 0; bj < 2; ++bj) {
;                     const int col = col0 + bj * 128;
;                     const u32x4 zw = zx[m][bj];
;                     f32x4 x0 = {bflo(zw.x), bfhi(zw.x), bflo(zw.y), bfhi(zw.y)}, x1 = {bflo(zw.z), bfhi(zw.z), bflo(zw.w), bfhi(zw.w)};
;                     if (pst) { const f32x4 g0 = *(const f32x4*)(pg + col), g1 = *(const f32x4*)(pg + col + 4), b0 = *(const f32x4*)(pb + col), b1 = *(const f32x4*)(pb + col + 4);
;                         x0 = (x0 - mu) * rstd * g0 + b0; x1 = (x1 - mu) * rstd * g1 + b1; }
;                     x0 = x0 * ALPHA + acc[ai][bj][m][0]; x1 = x1 * ALPHA + acc[ai][bj][m][1];
;                     if (Z) { float* p = Z + (size_t)row * 1024 + col; *(f32x4*)p = x0; *(f32x4*)(p + 4) = x1; }
;                     *(u32x4*)(ZB + (size_t)row * 1024 + col) = pack8(x0, x1);
.LBB0_1471:
	v_mov_b32_e32 v83, v82
	v_lshlrev_b32_e32 v92, 16, v118
	v_and_b32_e32 v93, 0xffff0000, v118
	v_lshlrev_b32_e32 v86, 16, v119
	v_and_b32_e32 v87, 0xffff0000, v119
	v_lshlrev_b32_e32 v88, 16, v120
	v_and_b32_e32 v89, 0xffff0000, v120
	v_lshlrev_b32_e32 v90, 16, v121
	s_and_b64 vcc, exec, s[40:41]
	v_and_b32_e32 v91, 0xffff0000, v121
	s_cbranch_vccnz .LBB0_1473
	ds_read_b128 v[94:97], v80 offset:1024
	ds_read_b128 v[98:101], v80
	ds_read_b128 v[102:105], v80 offset:16
	ds_read_b128 v[106:109], v80 offset:1040
	v_sub_f32_e32 v87, v87, v84
	v_sub_f32_e32 v86, v86, v84
	v_sub_f32_e32 v93, v93, v84
	v_sub_f32_e32 v92, v92, v84
	v_mov_b32_e32 v110, v82
	v_mov_b32_e32 v111, v82
	v_sub_f32_e32 v91, v91, v84
	v_sub_f32_e32 v90, v90, v84
	v_sub_f32_e32 v89, v89, v84
	v_sub_f32_e32 v88, v88, v84
	v_pk_mul_f32 v[92:93], v[82:83], v[92:93]
	v_pk_mul_f32 v[86:87], v[110:111], v[86:87]
	v_pk_mul_f32 v[88:89], v[82:83], v[88:89]
	v_pk_mul_f32 v[90:91], v[110:111], v[90:91]
	s_waitcnt lgkmcnt(0)
	v_pk_fma_f32 v[86:87], v[86:87], v[100:101], v[96:97]
	v_pk_fma_f32 v[92:93], v[92:93], v[98:99], v[94:95]
	s_nop 0
	v_pk_fma_f32 v[90:91], v[90:91], v[104:105], v[108:109]
	v_pk_fma_f32 v[88:89], v[88:89], v[102:103], v[106:107]
.LBB0_1473:
	v_pk_fma_f32 v[86:87], v[86:87], s[34:35], v[78:79] op_sel_hi:[1,0,1]
	v_pk_fma_f32 v[78:79], v[92:93], s[34:35], v[76:77] op_sel_hi:[1,0,1]
	v_pk_fma_f32 v[74:75], v[90:91], s[34:35], v[74:75] op_sel_hi:[1,0,1]
	v_pk_fma_f32 v[76:77], v[88:89], s[34:35], v[72:73] op_sel_hi:[1,0,1]
	v_lshl_add_u64 v[72:73], s[20:21], 0, v[180:181]
	v_cvt_pk_bf16_f32 v88, v78, v79
	v_cvt_pk_bf16_f32 v89, v86, v87
	v_cvt_pk_bf16_f32 v90, v76, v77
	v_cvt_pk_bf16_f32 v91, v74, v75
	v_lshl_add_u64 v[72:73], v[172:173], 1, v[72:73]
	global_store_dwordx4 v[72:73], v[88:91], off
	v_lshlrev_b32_e32 v92, 16, v114
	v_and_b32_e32 v93, 0xffff0000, v114
	v_lshlrev_b32_e32 v94, 16, v115
	v_and_b32_e32 v95, 0xffff0000, v115
	v_lshlrev_b32_e32 v88, 16, v116
	v_and_b32_e32 v89, 0xffff0000, v116
	v_lshlrev_b32_e32 v90, 16, v117
	s_and_b64 vcc, exec, s[40:41]
	v_and_b32_e32 v91, 0xffff0000, v117
	s_cbranch_vccnz .LBB0_1475
	ds_read_b128 v[96:99], v80 offset:1536
	ds_read_b128 v[100:103], v80 offset:512
	ds_read_b128 v[104:107], v80 offset:528
	ds_read_b128 v[108:111], v80 offset:1552
	v_sub_f32_e32 v95, v95, v84
	v_sub_f32_e32 v94, v94, v84
	v_sub_f32_e32 v93, v93, v84
	v_sub_f32_e32 v92, v92, v84
	v_mov_b32_e32 v112, v82
	v_mov_b32_e32 v113, v82
	v_sub_f32_e32 v91, v91, v84
	v_sub_f32_e32 v90, v90, v84
	s_waitcnt lgkmcnt(0)
	v_sub_f32_e32 v85, v89, v84
	v_sub_f32_e32 v84, v88, v84
	v_pk_mul_f32 v[88:89], v[82:83], v[92:93]
	v_pk_mul_f32 v[92:93], v[112:113], v[94:95]
	v_pk_mul_f32 v[82:83], v[82:83], v[84:85]
	v_pk_mul_f32 v[84:85], v[112:113], v[90:91]
	s_nop 0
	v_pk_fma_f32 v[94:95], v[92:93], v[102:103], v[98:99]
	v_pk_fma_f32 v[92:93], v[88:89], v[100:101], v[96:97]
	s_nop 0
	v_pk_fma_f32 v[90:91], v[84:85], v[106:107], v[110:111]
	v_pk_fma_f32 v[88:89], v[82:83], v[104:105], v[108:109]

; __device__ __forceinline__ float bflo(unsigned w) { return __uint_as_float(w << 16); }
; __device__ __forceinline__ float bfhi(unsigned w) { return __uint_as_float(w & 0xffff0000u); }
; __device__ __forceinline__ u32x4 pack8(f32x4 a, f32x4 b) { u32x4 w; w.x = cvtpk(a[0], a[1]); w.y = cvtpk(a[2], a[3]); w.z = cvtpk(b[0], b[1]); w.w = cvtpk(b[2], b[3]); return w; }
;     __device__ __forceinline__ void operator()(const pg8::f32x4 (&acc)[2][2][4][2], const pg8::Unit& u, int wr, int wc, int fr, int fq) const {
;     ...
;             for (int m = 0; m < 4; ++m) {
;                 const int rloc = ai * 128 + wr * 64 + m * 16 + fr, row = u.pm * 256 + rloc;
;                 float mu = 0.f, rstd = 1.f; if (pst) ln_row_stats(pst, rloc, mu, rstd);
;                 float s = 0.f, q = 0.f;
; #pragma unroll
;                 for (int bj = 0; bj < 2; ++bj) {
;                     const int col = col0 + bj * 128;
;                     const u32x4 zw = zx[m][bj];
;                     f32x4 x0 = {bflo(zw.x), bfhi(zw.x), bflo(zw.y), bfhi(zw.y)}, x1 = {bflo(zw.z), bfhi(zw.z), bflo(zw.w), bfhi(zw.w)};
;                     if (pst) { const f32x4 g0 = *(const f32x4*)(pg + col), g1 = *(const f32x4*)(pg + col + 4), b0 = *(const f32x4*)(pb + col), b1 = *(const f32x4*)(pb + col + 4);
;                         x0 = (x0 - mu) * rstd * g0 + b0; x1 = (x1 - mu) * rstd * g1 + b1; }
;                     x0 = x0 * ALPHA + acc[ai][bj][m][0]; x1 = x1 * ALPHA + acc[ai][bj][m][1];
;                     if (Z) { float* p = Z + (size_t)row * 1024 + col; *(f32x4*)p = x0; *(f32x4*)(p + 4) = x1; }
;                     *(u32x4*)(ZB + (size_t)row * 1024 + col) = pack8(x0, x1);
.LBB0_1480:
	v_mov_b32_e32 v113, v112
	s_waitcnt vmcnt(0)
	v_lshlrev_b32_e32 v120, 16, v94
	v_and_b32_e32 v121, 0xffff0000, v94
	v_lshlrev_b32_e32 v94, 16, v95
	v_and_b32_e32 v95, 0xffff0000, v95
	v_lshlrev_b32_e32 v118, 16, v96
	v_and_b32_e32 v119, 0xffff0000, v96
	v_lshlrev_b32_e32 v96, 16, v97
	s_and_b64 vcc, exec, s[40:41]
	v_and_b32_e32 v97, 0xffff0000, v97
	s_cbranch_vccnz .LBB0_1482
	ds_read_b128 v[122:125], v80 offset:1024
	ds_read_b128 v[126:129], v80
	ds_read_b128 v[130:133], v80 offset:16
	ds_read_b128 v[134:137], v80 offset:1040
	v_sub_f32_e32 v95, v95, v114
	v_sub_f32_e32 v94, v94, v114
	v_sub_f32_e32 v121, v121, v114
	v_sub_f32_e32 v120, v120, v114
	v_mov_b32_e32 v138, v112
	v_mov_b32_e32 v139, v112
	v_sub_f32_e32 v97, v97, v114
	v_sub_f32_e32 v96, v96, v114
	v_sub_f32_e32 v119, v119, v114
	v_sub_f32_e32 v118, v118, v114
	v_pk_mul_f32 v[120:121], v[112:113], v[120:121]
	v_pk_mul_f32 v[94:95], v[138:139], v[94:95]
	v_pk_mul_f32 v[118:119], v[112:113], v[118:119]
	v_pk_mul_f32 v[96:97], v[138:139], v[96:97]
	s_waitcnt lgkmcnt(0)
	v_pk_fma_f32 v[94:95], v[94:95], v[128:129], v[124:125]
	v_pk_fma_f32 v[120:121], v[120:121], v[126:127], v[122:123]
	s_nop 0
	v_pk_fma_f32 v[96:97], v[96:97], v[132:133], v[136:137]
	v_pk_fma_f32 v[118:119], v[118:119], v[130:131], v[134:135]
.LBB0_1482:
	v_pk_fma_f32 v[94:95], v[94:95], s[34:35], v[62:63] op_sel_hi:[1,0,1]
	v_pk_fma_f32 v[62:63], v[120:121], s[34:35], v[60:61] op_sel_hi:[1,0,1]
	v_pk_fma_f32 v[58:59], v[96:97], s[34:35], v[58:59] op_sel_hi:[1,0,1]
	v_pk_fma_f32 v[60:61], v[118:119], s[34:35], v[56:57] op_sel_hi:[1,0,1]
	v_lshl_add_u64 v[56:57], s[20:21], 0, v[116:117]
	v_cvt_pk_bf16_f32 v118, v62, v63
	v_cvt_pk_bf16_f32 v119, v94, v95
	v_cvt_pk_bf16_f32 v120, v60, v61
	v_cvt_pk_bf16_f32 v121, v58, v59
	v_lshl_add_u64 v[56:57], v[172:173], 1, v[56:57]
	s_nop 0
	v_lshlrev_b32_e32 v96, 16, v90
	v_and_b32_e32 v97, 0xffff0000, v90
	v_lshlrev_b32_e32 v116, 16, v91
	v_and_b32_e32 v117, 0xffff0000, v91
	v_lshlrev_b32_e32 v90, 16, v92
	v_and_b32_e32 v91, 0xffff0000, v92
	v_lshlrev_b32_e32 v92, 16, v93
	s_and_b64 vcc, exec, s[40:41]
	v_and_b32_e32 v93, 0xffff0000, v93
	global_store_dwordx4 v[56:57], v[118:121], off
	s_cbranch_vccnz .LBB0_1484
	ds_read_b128 v[118:121], v80 offset:1536
	ds_read_b128 v[122:125], v80 offset:512
	ds_read_b128 v[126:129], v80 offset:528
	ds_read_b128 v[130:133], v80 offset:1552
	v_sub_f32_e32 v117, v117, v114
	v_sub_f32_e32 v116, v116, v114
	v_sub_f32_e32 v97, v97, v114
	v_sub_f32_e32 v96, v96, v114
	v_mov_b32_e32 v134, v112
	v_mov_b32_e32 v135, v112
	v_sub_f32_e32 v93, v93, v114
	v_sub_f32_e32 v92, v92, v114
	v_sub_f32_e32 v91, v91, v114
	v_sub_f32_e32 v90, v90, v114
	v_pk_mul_f32 v[96:97], v[112:113], v[96:97]
	v_pk_mul_f32 v[114:115], v[134:135], v[116:117]
	v_pk_mul_f32 v[90:91], v[112:113], v[90:91]
	v_pk_mul_f32 v[92:93], v[134:135], v[92:93]
	s_waitcnt lgkmcnt(0)
	v_pk_fma_f32 v[116:117], v[114:115], v[124:125], v[120:121]
	v_pk_fma_f32 v[96:97], v[96:97], v[122:123], v[118:119]
	s_nop 0
	v_pk_fma_f32 v[92:93], v[92:93], v[128:129], v[132:133]
	v_pk_fma_f32 v[90:91], v[90:91], v[126:127], v[130:131]

; __device__ __forceinline__ float bflo(unsigned w) { return __uint_as_float(w << 16); }
; __device__ __forceinline__ float bfhi(unsigned w) { return __uint_as_float(w & 0xffff0000u); }
; __device__ __forceinline__ u32x4 pack8(f32x4 a, f32x4 b) { u32x4 w; w.x = cvtpk(a[0], a[1]); w.y = cvtpk(a[2], a[3]); w.z = cvtpk(b[0], b[1]); w.w = cvtpk(b[2], b[3]); return w; }
;     __device__ __forceinline__ void operator()(const pg8::f32x4 (&acc)[2][2][4][2], const pg8::Unit& u, int wr, int wc, int fr, int fq) const {
;     ...
;             for (int m = 0; m < 4; ++m) {
;                 const int rloc = ai * 128 + wr * 64 + m * 16 + fr, row = u.pm * 256 + rloc;
;                 float mu = 0.f, rstd = 1.f; if (pst) ln_row_stats(pst, rloc, mu, rstd);
;                 float s = 0.f, q = 0.f;
; #pragma unroll
;                 for (int bj = 0; bj < 2; ++bj) {
;                     const int col = col0 + bj * 128;
;                     const u32x4 zw = zx[m][bj];
;                     f32x4 x0 = {bflo(zw.x), bfhi(zw.x), bflo(zw.y), bfhi(zw.y)}, x1 = {bflo(zw.z), bfhi(zw.z), bflo(zw.w), bfhi(zw.w)};
;                     if (pst) { const f32x4 g0 = *(const f32x4*)(pg + col), g1 = *(const f32x4*)(pg + col + 4), b0 = *(const f32x4*)(pb + col), b1 = *(const f32x4*)(pb + col + 4);
;                         x0 = (x0 - mu) * rstd * g0 + b0; x1 = (x1 - mu) * rstd * g1 + b1; }
;                     x0 = x0 * ALPHA + acc[ai][bj][m][0]; x1 = x1 * ALPHA + acc[ai][bj][m][1];
;                     if (Z) { float* p = Z + (size_t)row * 1024 + col; *(f32x4*)p = x0; *(f32x4*)(p + 4) = x1; }
;                     *(u32x4*)(ZB + (size_t)row * 1024 + col) = pack8(x0, x1);
.LBB0_1489:
	v_mov_b32_e32 v49, v48
	s_nop 0
	v_lshlrev_b32_e32 v58, 16, v86
	v_and_b32_e32 v59, 0xffff0000, v86
	v_lshlrev_b32_e32 v52, 16, v87
	v_and_b32_e32 v53, 0xffff0000, v87
	v_lshlrev_b32_e32 v54, 16, v88
	v_and_b32_e32 v55, 0xffff0000, v88
	v_lshlrev_b32_e32 v56, 16, v89
	s_and_b64 vcc, exec, s[40:41]
	v_and_b32_e32 v57, 0xffff0000, v89
	s_cbranch_vccnz .LBB0_1491
	ds_read_b128 v[60:63], v80 offset:1024
	ds_read_b128 v[86:89], v80
	ds_read_b128 v[90:93], v80 offset:16
	ds_read_b128 v[94:97], v80 offset:1040
	v_sub_f32_e32 v53, v53, v50
	v_sub_f32_e32 v52, v52, v50
	v_sub_f32_e32 v59, v59, v50
	v_sub_f32_e32 v58, v58, v50
	v_mov_b32_e32 v110, v48
	v_mov_b32_e32 v111, v48
	v_sub_f32_e32 v57, v57, v50
	v_sub_f32_e32 v56, v56, v50
	v_sub_f32_e32 v55, v55, v50
	v_sub_f32_e32 v54, v54, v50
	v_pk_mul_f32 v[58:59], v[48:49], v[58:59]
	v_pk_mul_f32 v[52:53], v[110:111], v[52:53]
	v_pk_mul_f32 v[54:55], v[48:49], v[54:55]
	v_pk_mul_f32 v[56:57], v[110:111], v[56:57]
	s_waitcnt lgkmcnt(0)
	v_pk_fma_f32 v[52:53], v[52:53], v[88:89], v[62:63]
	v_pk_fma_f32 v[58:59], v[58:59], v[86:87], v[60:61]
	s_nop 0
	v_pk_fma_f32 v[56:57], v[56:57], v[92:93], v[96:97]
	v_pk_fma_f32 v[54:55], v[54:55], v[90:91], v[94:95]
.LBB0_1491:
	v_pk_fma_f32 v[52:53], v[52:53], s[34:35], v[46:47] op_sel_hi:[1,0,1]
	v_pk_fma_f32 v[46:47], v[58:59], s[34:35], v[44:45] op_sel_hi:[1,0,1]
	v_pk_fma_f32 v[42:43], v[56:57], s[34:35], v[42:43] op_sel_hi:[1,0,1]
	v_pk_fma_f32 v[44:45], v[54:55], s[34:35], v[40:41] op_sel_hi:[1,0,1]
	v_lshl_add_u64 v[40:41], s[20:21], 0, v[108:109]
	v_cvt_pk_bf16_f32 v54, v46, v47
	v_cvt_pk_bf16_f32 v55, v52, v53
	v_cvt_pk_bf16_f32 v56, v44, v45
	v_cvt_pk_bf16_f32 v57, v42, v43
	v_lshl_add_u64 v[40:41], v[172:173], 1, v[40:41]
	global_store_dwordx4 v[40:41], v[54:57], off
	s_nop 0
	v_lshlrev_b32_e32 v58, 16, v82
	v_and_b32_e32 v59, 0xffff0000, v82
	v_lshlrev_b32_e32 v60, 16, v83
	v_and_b32_e32 v61, 0xffff0000, v83
	v_lshlrev_b32_e32 v54, 16, v84
	v_and_b32_e32 v55, 0xffff0000, v84
	v_lshlrev_b32_e32 v56, 16, v85
	s_and_b64 vcc, exec, s[40:41]
	v_and_b32_e32 v57, 0xffff0000, v85
	s_cbranch_vccnz .LBB0_1493
	ds_read_b128 v[82:85], v80 offset:1536
	ds_read_b128 v[86:89], v80 offset:512
	ds_read_b128 v[90:93], v80 offset:528
	ds_read_b128 v[94:97], v80 offset:1552
	v_sub_f32_e32 v61, v61, v50
	v_sub_f32_e32 v60, v60, v50
	v_sub_f32_e32 v59, v59, v50
	v_sub_f32_e32 v58, v58, v50
	v_mov_b32_e32 v62, v48
	v_mov_b32_e32 v63, v48
	v_sub_f32_e32 v57, v57, v50
	v_sub_f32_e32 v56, v56, v50
	s_waitcnt lgkmcnt(0)
	v_sub_f32_e32 v51, v55, v50
	v_sub_f32_e32 v50, v54, v50
	v_pk_mul_f32 v[54:55], v[48:49], v[58:59]
	v_pk_mul_f32 v[58:59], v[62:63], v[60:61]
	v_pk_mul_f32 v[48:49], v[48:49], v[50:51]
	v_pk_mul_f32 v[50:51], v[62:63], v[56:57]
	s_nop 0
	v_pk_fma_f32 v[60:61], v[58:59], v[88:89], v[84:85]
	v_pk_fma_f32 v[58:59], v[54:55], v[86:87], v[82:83]
	s_nop 0
	v_pk_fma_f32 v[56:57], v[50:51], v[92:93], v[96:97]
	v_pk_fma_f32 v[54:55], v[48:49], v[90:91], v[94:95]

; __device__ __forceinline__ float bflo(unsigned w) { return __uint_as_float(w << 16); }
; __device__ __forceinline__ float bfhi(unsigned w) { return __uint_as_float(w & 0xffff0000u); }
; __device__ __forceinline__ u32x4 pack8(f32x4 a, f32x4 b) { u32x4 w; w.x = cvtpk(a[0], a[1]); w.y = cvtpk(a[2], a[3]); w.z = cvtpk(b[0], b[1]); w.w = cvtpk(b[2], b[3]); return w; }
;     __device__ __forceinline__ void operator()(const pg8::f32x4 (&acc)[2][2][4][2], const pg8::Unit& u, int wr, int wc, int fr, int fq) const {
;     ...
;             for (int m = 0; m < 4; ++m) {
;                 const int rloc = ai * 128 + wr * 64 + m * 16 + fr, row = u.pm * 256 + rloc;
;                 float mu = 0.f, rstd = 1.f; if (pst) ln_row_stats(pst, rloc, mu, rstd);
;                 float s = 0.f, q = 0.f;
; #pragma unroll
;                 for (int bj = 0; bj < 2; ++bj) {
;                     const int col = col0 + bj * 128;
;                     const u32x4 zw = zx[m][bj];
;                     f32x4 x0 = {bflo(zw.x), bfhi(zw.x), bflo(zw.y), bfhi(zw.y)}, x1 = {bflo(zw.z), bfhi(zw.z), bflo(zw.w), bfhi(zw.w)};
;                     if (pst) { const f32x4 g0 = *(const f32x4*)(pg + col), g1 = *(const f32x4*)(pg + col + 4), b0 = *(const f32x4*)(pb + col), b1 = *(const f32x4*)(pb + col + 4);
;                         x0 = (x0 - mu) * rstd * g0 + b0; x1 = (x1 - mu) * rstd * g1 + b1; }
;                     x0 = x0 * ALPHA + acc[ai][bj][m][0]; x1 = x1 * ALPHA + acc[ai][bj][m][1];
;                     if (Z) { float* p = Z + (size_t)row * 1024 + col; *(f32x4*)p = x0; *(f32x4*)(p + 4) = x1; }
;                     *(u32x4*)(ZB + (size_t)row * 1024 + col) = pack8(x0, x1);
.LBB0_1498:
	v_mov_b32_e32 v33, v32
	s_nop 0
	v_lshlrev_b32_e32 v42, 16, v76
	v_and_b32_e32 v43, 0xffff0000, v76
	v_lshlrev_b32_e32 v36, 16, v77
	v_and_b32_e32 v37, 0xffff0000, v77
	v_lshlrev_b32_e32 v38, 16, v78
	v_and_b32_e32 v39, 0xffff0000, v78
	v_lshlrev_b32_e32 v40, 16, v79
	s_and_b64 vcc, exec, s[40:41]
	v_and_b32_e32 v41, 0xffff0000, v79
	s_cbranch_vccnz .LBB0_1500
	ds_read_b128 v[44:47], v80 offset:1024
	ds_read_b128 v[48:51], v80
	ds_read_b128 v[52:55], v80 offset:16
	ds_read_b128 v[56:59], v80 offset:1040
	v_sub_f32_e32 v37, v37, v34
	v_sub_f32_e32 v36, v36, v34
	v_sub_f32_e32 v43, v43, v34
	v_sub_f32_e32 v42, v42, v34
	v_mov_b32_e32 v60, v32
	v_mov_b32_e32 v61, v32
	v_sub_f32_e32 v41, v41, v34
	v_sub_f32_e32 v40, v40, v34
	v_sub_f32_e32 v39, v39, v34
	v_sub_f32_e32 v38, v38, v34
	v_pk_mul_f32 v[42:43], v[32:33], v[42:43]
	v_pk_mul_f32 v[36:37], v[60:61], v[36:37]
	v_pk_mul_f32 v[38:39], v[32:33], v[38:39]
	v_pk_mul_f32 v[40:41], v[60:61], v[40:41]
	s_waitcnt lgkmcnt(0)
	v_pk_fma_f32 v[36:37], v[36:37], v[50:51], v[46:47]
	v_pk_fma_f32 v[42:43], v[42:43], v[48:49], v[44:45]
	s_nop 0
	v_pk_fma_f32 v[40:41], v[40:41], v[54:55], v[58:59]
	v_pk_fma_f32 v[38:39], v[38:39], v[52:53], v[56:57]
.LBB0_1500:
	v_pk_fma_f32 v[36:37], v[36:37], s[34:35], v[30:31] op_sel_hi:[1,0,1]
	v_pk_fma_f32 v[30:31], v[42:43], s[34:35], v[28:29] op_sel_hi:[1,0,1]
	v_pk_fma_f32 v[26:27], v[40:41], s[34:35], v[26:27] op_sel_hi:[1,0,1]
	v_pk_fma_f32 v[28:29], v[38:39], s[34:35], v[24:25] op_sel_hi:[1,0,1]
	v_lshl_add_u64 v[24:25], s[20:21], 0, v[104:105]
	v_cvt_pk_bf16_f32 v38, v30, v31
	v_cvt_pk_bf16_f32 v39, v36, v37
	v_cvt_pk_bf16_f32 v40, v28, v29
	v_cvt_pk_bf16_f32 v41, v26, v27
	v_lshl_add_u64 v[24:25], v[172:173], 1, v[24:25]
	global_store_dwordx4 v[24:25], v[38:41], off
	s_nop 0
	v_lshlrev_b32_e32 v42, 16, v72
	v_and_b32_e32 v43, 0xffff0000, v72
	v_lshlrev_b32_e32 v44, 16, v73
	v_and_b32_e32 v45, 0xffff0000, v73
	v_lshlrev_b32_e32 v38, 16, v74
	v_and_b32_e32 v39, 0xffff0000, v74
	v_lshlrev_b32_e32 v40, 16, v75
	s_and_b64 vcc, exec, s[40:41]
	v_and_b32_e32 v41, 0xffff0000, v75
	s_cbranch_vccnz .LBB0_1502
	ds_read_b128 v[46:49], v80 offset:1536
	ds_read_b128 v[50:53], v80 offset:512
	ds_read_b128 v[54:57], v80 offset:528
	ds_read_b128 v[58:61], v80 offset:1552
	v_sub_f32_e32 v45, v45, v34
	v_sub_f32_e32 v44, v44, v34
	v_sub_f32_e32 v43, v43, v34
	v_sub_f32_e32 v42, v42, v34
	v_mov_b32_e32 v62, v32
	v_mov_b32_e32 v63, v32
	v_sub_f32_e32 v41, v41, v34
	v_sub_f32_e32 v40, v40, v34
	s_waitcnt lgkmcnt(0)
	v_sub_f32_e32 v35, v39, v34
	v_sub_f32_e32 v34, v38, v34
	v_pk_mul_f32 v[38:39], v[32:33], v[42:43]
	v_pk_mul_f32 v[42:43], v[62:63], v[44:45]
	v_pk_mul_f32 v[32:33], v[32:33], v[34:35]
	v_pk_mul_f32 v[34:35], v[62:63], v[40:41]
	s_nop 0
	v_pk_fma_f32 v[44:45], v[42:43], v[52:53], v[48:49]
	v_pk_fma_f32 v[42:43], v[38:39], v[50:51], v[46:47]
	s_nop 0
	v_pk_fma_f32 v[40:41], v[34:35], v[56:57], v[60:61]
	v_pk_fma_f32 v[38:39], v[32:33], v[54:55], v[58:59]

; __device__ __forceinline__ float bflo(unsigned w) { return __uint_as_float(w << 16); }
; __device__ __forceinline__ float bfhi(unsigned w) { return __uint_as_float(w & 0xffff0000u); }
; __device__ __forceinline__ u32x4 pack8(f32x4 a, f32x4 b) { u32x4 w; w.x = cvtpk(a[0], a[1]); w.y = cvtpk(a[2], a[3]); w.z = cvtpk(b[0], b[1]); w.w = cvtpk(b[2], b[3]); return w; }
;     __device__ __forceinline__ void operator()(const pg8::f32x4 (&acc)[2][2][4][2], const pg8::Unit& u, int wr, int wc, int fr, int fq) const {
;     ...
;             for (int m = 0; m < 4; ++m) {
;                 const int rloc = ai * 128 + wr * 64 + m * 16 + fr, row = u.pm * 256 + rloc;
;                 float mu = 0.f, rstd = 1.f; if (pst) ln_row_stats(pst, rloc, mu, rstd);
;                 float s = 0.f, q = 0.f;
; #pragma unroll
;                 for (int bj = 0; bj < 2; ++bj) {
;                     const int col = col0 + bj * 128;
;                     const u32x4 zw = zx[m][bj];
;                     f32x4 x0 = {bflo(zw.x), bfhi(zw.x), bflo(zw.y), bfhi(zw.y)}, x1 = {bflo(zw.z), bfhi(zw.z), bflo(zw.w), bfhi(zw.w)};
;                     if (pst) { const f32x4 g0 = *(const f32x4*)(pg + col), g1 = *(const f32x4*)(pg + col + 4), b0 = *(const f32x4*)(pb + col), b1 = *(const f32x4*)(pb + col + 4);
;                         x0 = (x0 - mu) * rstd * g0 + b0; x1 = (x1 - mu) * rstd * g1 + b1; }
;                     x0 = x0 * ALPHA + acc[ai][bj][m][0]; x1 = x1 * ALPHA + acc[ai][bj][m][1];
;                     if (Z) { float* p = Z + (size_t)row * 1024 + col; *(f32x4*)p = x0; *(f32x4*)(p + 4) = x1; }
;                     *(u32x4*)(ZB + (size_t)row * 1024 + col) = pack8(x0, x1);
.LBB0_1507:
	v_mov_b32_e32 v17, v16
	s_nop 0
	v_lshlrev_b32_e32 v26, 16, v68
	v_and_b32_e32 v27, 0xffff0000, v68
	v_lshlrev_b32_e32 v20, 16, v69
	v_and_b32_e32 v21, 0xffff0000, v69
	v_lshlrev_b32_e32 v22, 16, v70
	v_and_b32_e32 v23, 0xffff0000, v70
	v_lshlrev_b32_e32 v24, 16, v71
	s_and_b64 vcc, exec, s[40:41]
	v_and_b32_e32 v25, 0xffff0000, v71
	s_cbranch_vccnz .LBB0_1509
	ds_read_b128 v[28:31], v80 offset:1024
	ds_read_b128 v[32:35], v80
	ds_read_b128 v[36:39], v80 offset:16
	ds_read_b128 v[40:43], v80 offset:1040
	v_sub_f32_e32 v21, v21, v18
	v_sub_f32_e32 v20, v20, v18
	v_sub_f32_e32 v27, v27, v18
	v_sub_f32_e32 v26, v26, v18
	v_mov_b32_e32 v44, v16
	v_mov_b32_e32 v45, v16
	v_sub_f32_e32 v25, v25, v18
	v_sub_f32_e32 v24, v24, v18
	v_sub_f32_e32 v23, v23, v18
	v_sub_f32_e32 v22, v22, v18
	v_pk_mul_f32 v[26:27], v[16:17], v[26:27]
	v_pk_mul_f32 v[20:21], v[44:45], v[20:21]
	v_pk_mul_f32 v[22:23], v[16:17], v[22:23]
	v_pk_mul_f32 v[24:25], v[44:45], v[24:25]
	s_waitcnt lgkmcnt(0)
	v_pk_fma_f32 v[20:21], v[20:21], v[34:35], v[30:31]
	v_pk_fma_f32 v[26:27], v[26:27], v[32:33], v[28:29]
	s_nop 0
	v_pk_fma_f32 v[24:25], v[24:25], v[38:39], v[42:43]
	v_pk_fma_f32 v[22:23], v[22:23], v[36:37], v[40:41]
.LBB0_1509:
	v_pk_fma_f32 v[20:21], v[20:21], s[34:35], v[14:15] op_sel_hi:[1,0,1]
	v_pk_fma_f32 v[14:15], v[26:27], s[34:35], v[12:13] op_sel_hi:[1,0,1]
	v_pk_fma_f32 v[10:11], v[24:25], s[34:35], v[10:11] op_sel_hi:[1,0,1]
	v_pk_fma_f32 v[12:13], v[22:23], s[34:35], v[8:9] op_sel_hi:[1,0,1]
	v_lshl_add_u64 v[8:9], s[20:21], 0, v[100:101]
	v_cvt_pk_bf16_f32 v22, v14, v15
	v_cvt_pk_bf16_f32 v23, v20, v21
	v_cvt_pk_bf16_f32 v24, v12, v13
	v_cvt_pk_bf16_f32 v25, v10, v11
	v_lshl_add_u64 v[8:9], v[172:173], 1, v[8:9]
	global_store_dwordx4 v[8:9], v[22:25], off
	s_nop 0
	v_lshlrev_b32_e32 v26, 16, v64
	v_and_b32_e32 v27, 0xffff0000, v64
	v_lshlrev_b32_e32 v28, 16, v65
	v_and_b32_e32 v29, 0xffff0000, v65
	v_lshlrev_b32_e32 v22, 16, v66
	v_and_b32_e32 v23, 0xffff0000, v66
	v_lshlrev_b32_e32 v24, 16, v67
	s_and_b64 vcc, exec, s[40:41]
	v_and_b32_e32 v25, 0xffff0000, v67
	s_cbranch_vccnz .LBB0_1511
	ds_read_b128 v[30:33], v80 offset:1536
	ds_read_b128 v[34:37], v80 offset:512
	ds_read_b128 v[38:41], v80 offset:528
	ds_read_b128 v[42:45], v80 offset:1552
	v_sub_f32_e32 v29, v29, v18
	v_sub_f32_e32 v28, v28, v18
	v_sub_f32_e32 v27, v27, v18
	v_sub_f32_e32 v26, v26, v18
	v_mov_b32_e32 v46, v16
	v_mov_b32_e32 v47, v16
	v_sub_f32_e32 v25, v25, v18
	v_sub_f32_e32 v24, v24, v18
	s_waitcnt lgkmcnt(0)
	v_sub_f32_e32 v19, v23, v18
	v_sub_f32_e32 v18, v22, v18
	v_pk_mul_f32 v[22:23], v[16:17], v[26:27]
	v_pk_mul_f32 v[26:27], v[46:47], v[28:29]
	v_pk_mul_f32 v[16:17], v[16:17], v[18:19]
	v_pk_mul_f32 v[18:19], v[46:47], v[24:25]
	s_nop 0
	v_pk_fma_f32 v[28:29], v[26:27], v[36:37], v[32:33]
	v_pk_fma_f32 v[26:27], v[22:23], v[34:35], v[30:31]
	s_nop 0
	v_pk_fma_f32 v[24:25], v[18:19], v[40:41], v[44:45]
	v_pk_fma_f32 v[22:23], v[16:17], v[38:39], v[42:43]

; __device__ __forceinline__ void ln_table(const float* st, int pm, int key, int wr, int wc, int fr, int fq) {
;     ...
;     if (st) {
;         const int want = key * 128 + pm + 1;
;         if (__builtin_amdgcn_readfirstlane(*kw) != want) {
;             if (t < 256) {
;                 const f32x4* p = (const f32x4*)(st + ((size_t)(pm * 256 + t)) * 32);
;                 float s = 0.f, q = 0.f;
; #pragma unroll
;                 for (int i = 0; i < 8; ++i) { const f32x4 v = p[i]; s += v[0] + v[2]; q += v[1] + v[3]; }
;                 const float mu = s * (1.f / D);
;                 tab[t] = (f32x2v){mu, __builtin_amdgcn_rsqf(fmaxf(q * (1.f / D) - mu * mu, 0.f) + LN_EPS)};
;     __device__ __forceinline__ void operator()(const pg8::f32x4 (&acc)[2][2][4][2], const pg8::Unit& u, int wr, int wc, int fr, int fq) const {
;     ...
;                 for (int bj = 0; bj < 2; ++bj) zx[m][bj] = *(const u32x4*)(ZB + (size_t)(u.pm * 256 + ai * 128 + wr * 64 + m * 16 + fr) * 1024 + col0 + bj * 128);
;             if (ai == 0) ln_table(pst, u.pm, key, wr, wc, fr, fq);
.LBB0_1692:
	v_mov_b32_e32 v197, v201
	v_mov_b32_e32 v205, v200
	s_lshl_b32 s0, s64, 8
	s_or_b32 s0, s0, s66
	s_lshl_b32 s3, s42, 8
	v_add_u32_e32 v196, s19, v197
	v_lshl_add_u32 v172, v205, 3, s0
	v_and_b32_e32 v186, 0xffffff00, v172
	v_and_b32_e32 v187, 0xff, v216
	v_add_lshl_u32 v186, v186, v187, 2
	v_mov_b32_e32 v187, 0
	v_cmp_gt_u32_e32 vcc, 0x100, v216
	v_mov_b32_e32 v188, s50
	v_mov_b32_e32 v189, s51
	s_and_saveexec_b64 vcc, vcc
	v_mov_b32_e32 v188, s48
	v_mov_b32_e32 v189, s49
	s_mov_b64 exec, vcc
	v_lshl_add_u64 v[188:189], v[188:189], 0, v[186:187]
	global_load_dword v186, v[188:189], off
	v_lshlrev_b32_e32 v187, 2, v216
	v_add_u32_e32 v187, 0x21000, v187
	v_and_b32_e32 v80, 0xff, v172
	v_lshlrev_b32_e32 v80, 2, v80
	v_add_u32_e32 v80, 0x21000, v80
	v_add_u32_e32 v176, s3, v196
	v_ashrrev_i32_e32 v173, 31, v172
	v_ashrrev_i32_e32 v177, 31, v176
	v_add_u32_e32 v190, 16, v176
	v_lshl_add_u64 v[174:175], v[172:173], 1, s[20:21]
	v_lshlrev_b64 v[194:195], 11, v[176:177]
	v_ashrrev_i32_e32 v191, 31, v190
	v_add_u32_e32 v182, 32, v176
	v_lshl_add_u64 v[90:91], v[174:175], 0, v[194:195]
	v_lshlrev_b64 v[192:193], 11, v[190:191]
	v_ashrrev_i32_e32 v183, 31, v182
	v_add_u32_e32 v178, 48, v176
	global_load_dwordx4 v[158:161], v[90:91], off
	global_load_dwordx4 v[154:157], v[90:91], off offset:256
	v_lshl_add_u64 v[90:91], v[174:175], 0, v[192:193]
	v_lshlrev_b64 v[184:185], 11, v[182:183]
	v_ashrrev_i32_e32 v179, 31, v178
	global_load_dwordx4 v[150:153], v[90:91], off
	global_load_dwordx4 v[138:141], v[90:91], off offset:256
	v_lshl_add_u64 v[90:91], v[174:175], 0, v[184:185]
	v_lshlrev_b64 v[180:181], 11, v[178:179]
	global_load_dwordx4 v[126:129], v[90:91], off
	global_load_dwordx4 v[114:117], v[90:91], off offset:256
	v_lshl_add_u64 v[90:91], v[174:175], 0, v[180:181]
	global_load_dwordx4 v[102:105], v[90:91], off
	s_nop 0
	global_load_dwordx4 v[90:93], v[90:91], off offset:256
	s_waitcnt vmcnt(8)
	ds_write_b32 v187, v186
	ds_read_b32 v186, v223
	s_add_i32 s2, s73, s42
	s_waitcnt lgkmcnt(0)
	v_readfirstlane_b32 s0, v186
	s_cmp_eq_u32 s0, s2
	s_cbranch_scc1 .LBB0_1698
	v_lshlrev_b32_e32 v186, 4, v205
	v_add3_u32 v197, s69, v197, v186
	s_movk_i32 s0, 0x100
	v_cmp_gt_i32_e32 vcc, s0, v197
	s_and_saveexec_b64 s[0:1], vcc
	s_cbranch_execz .LBB0_1695
	v_add_u32_e32 v186, s3, v197
	v_ashrrev_i32_e32 v187, 31, v186
	v_lshlrev_b64 v[186:187], 7, v[186:187]
	v_lshl_add_u64 v[198:199], s[44:45], 0, v[186:187]
	global_load_dwordx4 v[186:189], v[198:199], off
	global_load_dwordx4 v[206:209], v[198:199], off offset:16
	global_load_dwordx4 v[210:213], v[198:199], off offset:32
	global_load_dwordx4 v[226:229], v[198:199], off offset:48
	global_load_dwordx4 v[234:237], v[198:199], off offset:64
	global_load_dwordx4 v[238:241], v[198:199], off offset:80
	global_load_dwordx4 v[242:245], v[198:199], off offset:96
	global_load_dwordx4 v[246:249], v[198:199], off offset:112
	s_mov_b32 s4, 0x3a800000
	s_waitcnt vmcnt(0)
	v_pk_add_f32 v[186:187], v[186:187], v[188:189]
	v_pk_add_f32 v[188:189], v[206:207], v[208:209]
	v_pk_add_f32 v[186:187], v[186:187], 0 op_sel_hi:[1,0]
	v_pk_add_f32 v[198:199], v[210:211], v[212:213]
	v_pk_add_f32 v[186:187], v[186:187], v[188:189]
	v_pk_add_f32 v[206:207], v[226:227], v[228:229]
	v_pk_add_f32 v[186:187], v[186:187], v[198:199]
	v_pk_add_f32 v[208:209], v[234:235], v[236:237]
	v_pk_add_f32 v[186:187], v[186:187], v[206:207]
	v_pk_add_f32 v[210:211], v[238:239], v[240:241]
	v_pk_add_f32 v[186:187], v[186:187], v[208:209]
	v_pk_add_f32 v[212:213], v[242:243], v[244:245]
	v_pk_add_f32 v[186:187], v[186:187], v[210:211]
	v_pk_add_f32 v[188:189], v[246:247], v[248:249]
	v_pk_add_f32 v[186:187], v[186:187], v[212:213]
	s_nop 0
	v_pk_add_f32 v[186:187], v[186:187], v[188:189]
	v_lshl_add_u32 v188, v197, 3, v225
	v_pk_mul_f32 v[186:187], v[186:187], s[4:5] op_sel_hi:[1,0]
	s_nop 0
	v_fma_f32 v187, -v186, v186, v187
	v_max_f32_e32 v187, 0, v187
	v_add_f32_e32 v187, 0x3727c5ac, v187
	v_rsq_f32_e32 v187, v187
	ds_write_b64 v188, v[186:187]

; __device__ __forceinline__ float bflo(unsigned w) { return __uint_as_float(w << 16); }
; __device__ __forceinline__ float bfhi(unsigned w) { return __uint_as_float(w & 0xffff0000u); }
; __device__ __forceinline__ u32x4 pack8(f32x4 a, f32x4 b) { u32x4 w; w.x = cvtpk(a[0], a[1]); w.y = cvtpk(a[2], a[3]); w.z = cvtpk(b[0], b[1]); w.w = cvtpk(b[2], b[3]); return w; }
;     __device__ __forceinline__ void operator()(const pg8::f32x4 (&acc)[2][2][4][2], const pg8::Unit& u, int wr, int wc, int fr, int fq) const {
;     ...
;             for (int m = 0; m < 4; ++m) {
;                 const int rloc = ai * 128 + wr * 64 + m * 16 + fr, row = u.pm * 256 + rloc;
;                 float mu = 0.f, rstd = 1.f; if (pst) ln_row_stats(pst, rloc, mu, rstd);
;                 float s = 0.f, q = 0.f;
; #pragma unroll
;                 for (int bj = 0; bj < 2; ++bj) {
;                     const int col = col0 + bj * 128;
;                     const u32x4 zw = zx[m][bj];
;                     f32x4 x0 = {bflo(zw.x), bfhi(zw.x), bflo(zw.y), bfhi(zw.y)}, x1 = {bflo(zw.z), bfhi(zw.z), bflo(zw.w), bfhi(zw.w)};
;                     if (pst) { const f32x4 g0 = *(const f32x4*)(pg + col), g1 = *(const f32x4*)(pg + col + 4), b0 = *(const f32x4*)(pb + col), b1 = *(const f32x4*)(pb + col + 4);
;                         x0 = (x0 - mu) * rstd * g0 + b0; x1 = (x1 - mu) * rstd * g1 + b1; }
;                     x0 = x0 * ALPHA + acc[ai][bj][m][0]; x1 = x1 * ALPHA + acc[ai][bj][m][1];
;                     if (Z) { float* p = Z + (size_t)row * 1024 + col; *(f32x4*)p = x0; *(f32x4*)(p + 4) = x1; }
;                     *(u32x4*)(ZB + (size_t)row * 1024 + col) = pack8(x0, x1);
.LBB0_1698:
	s_waitcnt vmcnt(0)
	s_waitcnt lgkmcnt(0)
	s_barrier
	v_lshlrev_b32_e32 v214, 16, v158
	v_and_b32_e32 v215, 0xffff0000, v158
	v_lshlrev_b32_e32 v224, 16, v159
	v_and_b32_e32 v234, 0xffff0000, v159
	v_lshlrev_b64 v[158:159], 2, v[172:173]
	v_lshl_add_u32 v204, v196, 3, v225
	v_lshlrev_b32_e32 v236, 16, v160
	v_and_b32_e32 v237, 0xffff0000, v160
	v_lshlrev_b32_e32 v238, 16, v161
	v_and_b32_e32 v239, 0xffff0000, v161
	v_lshl_add_u64 v[160:161], s[48:49], 0, v[158:159]
	v_lshl_add_u64 v[158:159], s[50:51], 0, v[158:159]
	ds_read_b64 v[196:197], v204
	ds_read_b128 v[186:189], v80 offset:16
	ds_read_b128 v[206:209], v80
	ds_read_b128 v[210:213], v80 offset:1040
	ds_read_b128 v[226:229], v80 offset:1024
	v_lshlrev_b64 v[198:199], 12, v[176:177]
	s_andn2_b64 vcc, exec, s[46:47]
	s_waitcnt lgkmcnt(0)
	v_sub_f32_e32 v215, v215, v196
	v_sub_f32_e32 v214, v214, v196
	v_pk_mul_f32 v[214:215], v[196:197], v[214:215] op_sel:[1,0]
	v_sub_f32_e32 v235, v234, v196
	v_sub_f32_e32 v234, v224, v196
	v_pk_mul_f32 v[234:235], v[196:197], v[234:235] op_sel:[1,0]
	s_nop 0
	v_pk_fma_f32 v[206:207], v[206:207], v[214:215], v[226:227]
	v_sub_f32_e32 v215, v237, v196
	v_sub_f32_e32 v214, v236, v196
	v_pk_mul_f32 v[214:215], v[196:197], v[214:215] op_sel:[1,0]
	v_sub_f32_e32 v227, v239, v196
	v_sub_f32_e32 v226, v238, v196
	v_pk_fma_f32 v[186:187], v[186:187], v[214:215], v[210:211]
	v_pk_mul_f32 v[226:227], v[196:197], v[226:227] op_sel:[1,0]
	v_pk_fma_f32 v[142:143], v[186:187], s[34:35], v[142:143] op_sel_hi:[1,0,1]
	v_cndmask_b32_e64 v186, 0, 1, s[46:47]
	v_pk_fma_f32 v[208:209], v[208:209], v[234:235], v[228:229]
	v_pk_fma_f32 v[188:189], v[188:189], v[226:227], v[212:213]
	v_cmp_ne_u32_e64 s[40:41], 1, v186
	v_lshl_add_u64 v[186:187], s[96:97], 0, v[198:199]
	v_pk_fma_f32 v[148:149], v[208:209], s[34:35], v[148:149] op_sel_hi:[1,0,1]
	v_pk_fma_f32 v[146:147], v[206:207], s[34:35], v[146:147] op_sel_hi:[1,0,1]
	v_pk_fma_f32 v[144:145], v[188:189], s[34:35], v[144:145] op_sel_hi:[1,0,1]
	v_lshl_add_u64 v[198:199], v[172:173], 2, v[186:187]
	s_cbranch_vccnz .LBB0_1700
	global_store_dwordx4 v[198:199], v[146:149], off
	global_store_dwordx4 v[198:199], v[142:145], off offset:16
.LBB0_1700:
	v_lshl_add_u64 v[194:195], s[20:21], 0, v[194:195]
	v_cvt_pk_bf16_f32 v186, v146, v147
	v_cvt_pk_bf16_f32 v187, v148, v149
	v_cvt_pk_bf16_f32 v188, v142, v143
	v_cvt_pk_bf16_f32 v189, v144, v145
	v_lshl_add_u64 v[194:195], v[172:173], 1, v[194:195]
	global_store_dwordx4 v[194:195], v[186:189], off
	ds_read_b128 v[186:189], v80 offset:1536
	s_nop 0
	ds_read_b128 v[206:209], v80 offset:512
	ds_read_b128 v[210:213], v80 offset:528
	ds_read_b128 v[226:229], v80 offset:1552
	v_lshlrev_b32_e32 v224, 16, v154
	v_and_b32_e32 v234, 0xffff0000, v154
	v_lshlrev_b32_e32 v235, 16, v155
	v_and_b32_e32 v236, 0xffff0000, v155
	v_lshlrev_b32_e32 v238, 16, v156
	v_and_b32_e32 v239, 0xffff0000, v156
	v_lshlrev_b32_e32 v240, 16, v157
	v_and_b32_e32 v237, 0xffff0000, v157
	v_mov_b32_e32 v214, v197
	v_mov_b32_e32 v215, v197
	v_mov_b32_e32 v154, v197
	v_mov_b32_e32 v155, v197
	v_sub_f32_e32 v157, v236, v196
	v_sub_f32_e32 v156, v235, v196
	v_sub_f32_e32 v235, v234, v196
	v_sub_f32_e32 v234, v224, v196
	v_sub_f32_e32 v237, v237, v196
	v_sub_f32_e32 v236, v240, v196
	v_sub_f32_e32 v197, v239, v196
	v_sub_f32_e32 v196, v238, v196
	v_pk_mul_f32 v[234:235], v[214:215], v[234:235]
	v_pk_mul_f32 v[156:157], v[154:155], v[156:157]
	v_pk_mul_f32 v[196:197], v[214:215], v[196:197]
	v_pk_mul_f32 v[154:155], v[154:155], v[236:237]
	s_and_b64 vcc, exec, s[40:41]
	s_waitcnt lgkmcnt(0)
	v_pk_fma_f32 v[156:157], v[156:157], v[208:209], v[188:189]
	v_pk_fma_f32 v[186:187], v[234:235], v[206:207], v[186:187]
	s_nop 0
	v_pk_fma_f32 v[154:155], v[154:155], v[212:213], v[228:229]
	v_pk_fma_f32 v[188:189], v[196:197], v[210:211], v[226:227]
	v_pk_fma_f32 v[134:135], v[186:187], s[34:35], v[134:135] op_sel_hi:[1,0,1]
	v_pk_fma_f32 v[136:137], v[156:157], s[34:35], v[136:137] op_sel_hi:[1,0,1]
	v_pk_fma_f32 v[130:131], v[188:189], s[34:35], v[130:131] op_sel_hi:[1,0,1]
	v_pk_fma_f32 v[132:133], v[154:155], s[34:35], v[132:133] op_sel_hi:[1,0,1]
	s_cbranch_vccnz .LBB0_1702
	global_store_dwordx4 v[198:199], v[134:137], off offset:512
	global_store_dwordx4 v[198:199], v[130:133], off offset:528

; __device__ __forceinline__ float bflo(unsigned w) { return __uint_as_float(w << 16); }
; __device__ __forceinline__ float bfhi(unsigned w) { return __uint_as_float(w & 0xffff0000u); }
; __device__ __forceinline__ u32x4 pack8(f32x4 a, f32x4 b) { u32x4 w; w.x = cvtpk(a[0], a[1]); w.y = cvtpk(a[2], a[3]); w.z = cvtpk(b[0], b[1]); w.w = cvtpk(b[2], b[3]); return w; }
;     __device__ __forceinline__ void operator()(const pg8::f32x4 (&acc)[2][2][4][2], const pg8::Unit& u, int wr, int wc, int fr, int fq) const {
;     ...
;             for (int m = 0; m < 4; ++m) {
;                 const int rloc = ai * 128 + wr * 64 + m * 16 + fr, row = u.pm * 256 + rloc;
;                 float mu = 0.f, rstd = 1.f; if (pst) ln_row_stats(pst, rloc, mu, rstd);
;                 float s = 0.f, q = 0.f;
; #pragma unroll
;                 for (int bj = 0; bj < 2; ++bj) {
;                     const int col = col0 + bj * 128;
;                     const u32x4 zw = zx[m][bj];
;                     f32x4 x0 = {bflo(zw.x), bfhi(zw.x), bflo(zw.y), bfhi(zw.y)}, x1 = {bflo(zw.z), bfhi(zw.z), bflo(zw.w), bfhi(zw.w)};
;                     if (pst) { const f32x4 g0 = *(const f32x4*)(pg + col), g1 = *(const f32x4*)(pg + col + 4), b0 = *(const f32x4*)(pb + col), b1 = *(const f32x4*)(pb + col + 4);
;                         x0 = (x0 - mu) * rstd * g0 + b0; x1 = (x1 - mu) * rstd * g1 + b1; }
;                     x0 = x0 * ALPHA + acc[ai][bj][m][0]; x1 = x1 * ALPHA + acc[ai][bj][m][1];
;                     if (Z) { float* p = Z + (size_t)row * 1024 + col; *(f32x4*)p = x0; *(f32x4*)(p + 4) = x1; }
;                     *(u32x4*)(ZB + (size_t)row * 1024 + col) = pack8(x0, x1);
.LBB0_1704:
	s_or_b64 exec, exec, s[0:1]
	ds_read_b64 v[130:131], v204 offset:128
	v_lshlrev_b32_e32 v154, 16, v150
	v_and_b32_e32 v155, 0xffff0000, v150
	v_lshlrev_b32_e32 v156, 16, v151
	v_and_b32_e32 v157, 0xffff0000, v151
	v_lshlrev_b32_e32 v177, 16, v152
	v_and_b32_e32 v186, 0xffff0000, v152
	v_lshlrev_b32_e32 v187, 16, v153
	v_and_b32_e32 v188, 0xffff0000, v153
	ds_read_b128 v[132:135], v80 offset:16
	s_waitcnt lgkmcnt(1)
	ds_read_b128 v[142:145], v80
	ds_read_b128 v[146:149], v80 offset:1040
	ds_read_b128 v[150:153], v80 offset:1024
	s_waitcnt lgkmcnt(0)
	v_sub_f32_e32 v155, v155, v130
	v_sub_f32_e32 v154, v154, v130
	v_sub_f32_e32 v157, v157, v130
	v_sub_f32_e32 v156, v156, v130
	v_pk_mul_f32 v[154:155], v[130:131], v[154:155] op_sel:[1,0]
	v_pk_mul_f32 v[156:157], v[130:131], v[156:157] op_sel:[1,0]
	v_lshlrev_b64 v[136:137], 12, v[190:191]
	s_and_b64 vcc, exec, s[40:41]
	s_nop 0
	v_pk_fma_f32 v[142:143], v[142:143], v[154:155], v[150:151]
	v_sub_f32_e32 v151, v186, v130
	v_sub_f32_e32 v150, v177, v130
	v_pk_fma_f32 v[144:145], v[144:145], v[156:157], v[152:153]
	v_sub_f32_e32 v153, v188, v130
	v_sub_f32_e32 v152, v187, v130
	v_pk_mul_f32 v[150:151], v[130:131], v[150:151] op_sel:[1,0]
	v_pk_mul_f32 v[152:153], v[130:131], v[152:153] op_sel:[1,0]
	v_pk_fma_f32 v[132:133], v[132:133], v[150:151], v[146:147]
	v_pk_fma_f32 v[134:135], v[134:135], v[152:153], v[148:149]
	v_pk_fma_f32 v[118:119], v[132:133], s[34:35], v[118:119] op_sel_hi:[1,0,1]
	v_lshl_add_u64 v[132:133], s[96:97], 0, v[136:137]
	v_pk_fma_f32 v[124:125], v[144:145], s[34:35], v[124:125] op_sel_hi:[1,0,1]
	v_pk_fma_f32 v[122:123], v[142:143], s[34:35], v[122:123] op_sel_hi:[1,0,1]
	v_pk_fma_f32 v[120:121], v[134:135], s[34:35], v[120:121] op_sel_hi:[1,0,1]
	v_lshl_add_u64 v[134:135], v[172:173], 2, v[132:133]
	s_cbranch_vccnz .LBB0_1706
	global_store_dwordx4 v[134:135], v[122:125], off
	global_store_dwordx4 v[134:135], v[118:121], off offset:16
.LBB0_1706:
	v_lshl_add_u64 v[132:133], s[20:21], 0, v[192:193]
	v_cvt_pk_bf16_f32 v142, v122, v123
	v_cvt_pk_bf16_f32 v143, v124, v125
	v_cvt_pk_bf16_f32 v144, v118, v119
	v_cvt_pk_bf16_f32 v145, v120, v121
	v_lshl_add_u64 v[132:133], v[172:173], 1, v[132:133]
	global_store_dwordx4 v[132:133], v[142:145], off
	v_lshlrev_b32_e32 v156, 16, v138
	v_and_b32_e32 v157, 0xffff0000, v138
	v_lshlrev_b32_e32 v154, 16, v139
	v_and_b32_e32 v155, 0xffff0000, v139
	v_lshlrev_b32_e32 v177, 16, v140
	v_and_b32_e32 v188, 0xffff0000, v140
	v_lshlrev_b32_e32 v189, 16, v141
	v_and_b32_e32 v192, 0xffff0000, v141
	ds_read_b128 v[136:139], v80 offset:528
	ds_read_b128 v[140:143], v80 offset:512
	ds_read_b128 v[144:147], v80 offset:1552
	ds_read_b128 v[148:151], v80 offset:1536
	v_mov_b32_e32 v152, v131
	v_mov_b32_e32 v153, v131
	v_sub_f32_e32 v157, v157, v130
	v_sub_f32_e32 v156, v156, v130
	v_pk_mul_f32 v[156:157], v[152:153], v[156:157]
	v_sub_f32_e32 v155, v155, v130
	v_sub_f32_e32 v154, v154, v130
	v_mov_b32_e32 v186, v131
	v_mov_b32_e32 v187, v131
	v_sub_f32_e32 v131, v188, v130
	v_pk_mul_f32 v[154:155], v[186:187], v[154:155]
	s_and_b64 vcc, exec, s[40:41]
	s_waitcnt lgkmcnt(0)
	v_pk_fma_f32 v[140:141], v[156:157], v[140:141], v[148:149]
	v_sub_f32_e32 v149, v192, v130
	v_sub_f32_e32 v148, v189, v130
	v_sub_f32_e32 v130, v177, v130
	v_pk_mul_f32 v[130:131], v[152:153], v[130:131]
	v_pk_mul_f32 v[148:149], v[186:187], v[148:149]
	v_pk_fma_f32 v[142:143], v[154:155], v[142:143], v[150:151]
	v_pk_fma_f32 v[138:139], v[148:149], v[138:139], v[146:147]
	v_pk_fma_f32 v[130:131], v[130:131], v[136:137], v[144:145]
	v_pk_fma_f32 v[110:111], v[140:141], s[34:35], v[110:111] op_sel_hi:[1,0,1]
	v_pk_fma_f32 v[112:113], v[142:143], s[34:35], v[112:113] op_sel_hi:[1,0,1]
	v_pk_fma_f32 v[106:107], v[130:131], s[34:35], v[106:107] op_sel_hi:[1,0,1]
	v_pk_fma_f32 v[108:109], v[138:139], s[34:35], v[108:109] op_sel_hi:[1,0,1]
	s_cbranch_vccnz .LBB0_1708
	global_store_dwordx4 v[134:135], v[110:113], off offset:512
	global_store_dwordx4 v[134:135], v[106:109], off offset:528

; __device__ __forceinline__ float bflo(unsigned w) { return __uint_as_float(w << 16); }
; __device__ __forceinline__ float bfhi(unsigned w) { return __uint_as_float(w & 0xffff0000u); }
; __device__ __forceinline__ u32x4 pack8(f32x4 a, f32x4 b) { u32x4 w; w.x = cvtpk(a[0], a[1]); w.y = cvtpk(a[2], a[3]); w.z = cvtpk(b[0], b[1]); w.w = cvtpk(b[2], b[3]); return w; }
;     __device__ __forceinline__ void operator()(const pg8::f32x4 (&acc)[2][2][4][2], const pg8::Unit& u, int wr, int wc, int fr, int fq) const {
;     ...
;             for (int m = 0; m < 4; ++m) {
;                 const int rloc = ai * 128 + wr * 64 + m * 16 + fr, row = u.pm * 256 + rloc;
;                 float mu = 0.f, rstd = 1.f; if (pst) ln_row_stats(pst, rloc, mu, rstd);
;                 float s = 0.f, q = 0.f;
; #pragma unroll
;                 for (int bj = 0; bj < 2; ++bj) {
;                     const int col = col0 + bj * 128;
;                     const u32x4 zw = zx[m][bj];
;                     f32x4 x0 = {bflo(zw.x), bfhi(zw.x), bflo(zw.y), bfhi(zw.y)}, x1 = {bflo(zw.z), bfhi(zw.z), bflo(zw.w), bfhi(zw.w)};
;                     if (pst) { const f32x4 g0 = *(const f32x4*)(pg + col), g1 = *(const f32x4*)(pg + col + 4), b0 = *(const f32x4*)(pb + col), b1 = *(const f32x4*)(pb + col + 4);
;                         x0 = (x0 - mu) * rstd * g0 + b0; x1 = (x1 - mu) * rstd * g1 + b1; }
;                     x0 = x0 * ALPHA + acc[ai][bj][m][0]; x1 = x1 * ALPHA + acc[ai][bj][m][1];
;                     if (Z) { float* p = Z + (size_t)row * 1024 + col; *(f32x4*)p = x0; *(f32x4*)(p + 4) = x1; }
;                     *(u32x4*)(ZB + (size_t)row * 1024 + col) = pack8(x0, x1);
.LBB0_1710:
	s_or_b64 exec, exec, s[0:1]
	ds_read_b64 v[106:107], v204 offset:256
	v_lshlrev_b32_e32 v130, 16, v126
	v_and_b32_e32 v131, 0xffff0000, v126
	v_lshlrev_b32_e32 v132, 16, v127
	v_and_b32_e32 v133, 0xffff0000, v127
	v_lshlrev_b32_e32 v134, 16, v128
	v_and_b32_e32 v135, 0xffff0000, v128
	v_lshlrev_b32_e32 v136, 16, v129
	v_and_b32_e32 v137, 0xffff0000, v129
	ds_read_b128 v[108:111], v80 offset:16
	s_waitcnt lgkmcnt(1)
	ds_read_b128 v[118:121], v80
	ds_read_b128 v[122:125], v80 offset:1040
	ds_read_b128 v[126:129], v80 offset:1024
	s_waitcnt lgkmcnt(0)
	v_sub_f32_e32 v131, v131, v106
	v_sub_f32_e32 v130, v130, v106
	v_sub_f32_e32 v133, v133, v106
	v_sub_f32_e32 v132, v132, v106
	v_pk_mul_f32 v[130:131], v[106:107], v[130:131] op_sel:[1,0]
	v_pk_mul_f32 v[132:133], v[106:107], v[132:133] op_sel:[1,0]
	v_lshlrev_b64 v[112:113], 12, v[182:183]
	s_and_b64 vcc, exec, s[40:41]
	s_nop 0
	v_pk_fma_f32 v[118:119], v[118:119], v[130:131], v[126:127]
	v_sub_f32_e32 v127, v135, v106
	v_sub_f32_e32 v126, v134, v106
	v_pk_fma_f32 v[120:121], v[120:121], v[132:133], v[128:129]
	v_sub_f32_e32 v129, v137, v106
	v_sub_f32_e32 v128, v136, v106
	v_pk_mul_f32 v[126:127], v[106:107], v[126:127] op_sel:[1,0]
	v_pk_mul_f32 v[128:129], v[106:107], v[128:129] op_sel:[1,0]
	v_pk_fma_f32 v[108:109], v[108:109], v[126:127], v[122:123]
	v_pk_fma_f32 v[110:111], v[110:111], v[128:129], v[124:125]
	v_pk_fma_f32 v[94:95], v[108:109], s[34:35], v[94:95] op_sel_hi:[1,0,1]
	v_lshl_add_u64 v[108:109], s[96:97], 0, v[112:113]
	v_pk_fma_f32 v[100:101], v[120:121], s[34:35], v[100:101] op_sel_hi:[1,0,1]
	v_pk_fma_f32 v[98:99], v[118:119], s[34:35], v[98:99] op_sel_hi:[1,0,1]
	v_pk_fma_f32 v[96:97], v[110:111], s[34:35], v[96:97] op_sel_hi:[1,0,1]
	v_lshl_add_u64 v[110:111], v[172:173], 2, v[108:109]
	s_cbranch_vccnz .LBB0_1712
	global_store_dwordx4 v[110:111], v[98:101], off
	global_store_dwordx4 v[110:111], v[94:97], off offset:16
.LBB0_1712:
	v_lshl_add_u64 v[108:109], s[20:21], 0, v[184:185]
	v_cvt_pk_bf16_f32 v118, v98, v99
	v_cvt_pk_bf16_f32 v119, v100, v101
	v_cvt_pk_bf16_f32 v120, v94, v95
	v_cvt_pk_bf16_f32 v121, v96, v97
	v_lshl_add_u64 v[108:109], v[172:173], 1, v[108:109]
	global_store_dwordx4 v[108:109], v[118:121], off
	v_lshlrev_b32_e32 v132, 16, v114
	v_and_b32_e32 v133, 0xffff0000, v114
	v_lshlrev_b32_e32 v130, 16, v115
	v_and_b32_e32 v131, 0xffff0000, v115
	v_lshlrev_b32_e32 v136, 16, v116
	v_and_b32_e32 v137, 0xffff0000, v116
	v_lshlrev_b32_e32 v138, 16, v117
	v_and_b32_e32 v139, 0xffff0000, v117
	ds_read_b128 v[112:115], v80 offset:528
	ds_read_b128 v[116:119], v80 offset:512
	ds_read_b128 v[120:123], v80 offset:1552
	ds_read_b128 v[124:127], v80 offset:1536
	v_mov_b32_e32 v128, v107
	v_mov_b32_e32 v129, v107
	v_sub_f32_e32 v133, v133, v106
	v_sub_f32_e32 v132, v132, v106
	v_pk_mul_f32 v[132:133], v[128:129], v[132:133]
	v_sub_f32_e32 v131, v131, v106
	v_sub_f32_e32 v130, v130, v106
	v_mov_b32_e32 v134, v107
	v_mov_b32_e32 v135, v107
	v_sub_f32_e32 v107, v137, v106
	v_pk_mul_f32 v[130:131], v[134:135], v[130:131]
	s_and_b64 vcc, exec, s[40:41]
	s_waitcnt lgkmcnt(0)
	v_pk_fma_f32 v[116:117], v[132:133], v[116:117], v[124:125]
	v_sub_f32_e32 v125, v139, v106
	v_sub_f32_e32 v124, v138, v106
	v_sub_f32_e32 v106, v136, v106
	v_pk_mul_f32 v[106:107], v[128:129], v[106:107]
	v_pk_mul_f32 v[124:125], v[134:135], v[124:125]
	v_pk_fma_f32 v[118:119], v[130:131], v[118:119], v[126:127]
	v_pk_fma_f32 v[114:115], v[124:125], v[114:115], v[122:123]
	v_pk_fma_f32 v[106:107], v[106:107], v[112:113], v[120:121]
	v_pk_fma_f32 v[86:87], v[116:117], s[34:35], v[86:87] op_sel_hi:[1,0,1]
	v_pk_fma_f32 v[88:89], v[118:119], s[34:35], v[88:89] op_sel_hi:[1,0,1]
	v_pk_fma_f32 v[82:83], v[106:107], s[34:35], v[82:83] op_sel_hi:[1,0,1]
	v_pk_fma_f32 v[84:85], v[114:115], s[34:35], v[84:85] op_sel_hi:[1,0,1]
	s_cbranch_vccnz .LBB0_1714
	global_store_dwordx4 v[110:111], v[86:89], off offset:512
	global_store_dwordx4 v[110:111], v[82:85], off offset:528

; __device__ __forceinline__ float bflo(unsigned w) { return __uint_as_float(w << 16); }
; __device__ __forceinline__ float bfhi(unsigned w) { return __uint_as_float(w & 0xffff0000u); }
; __device__ __forceinline__ u32x4 pack8(f32x4 a, f32x4 b) { u32x4 w; w.x = cvtpk(a[0], a[1]); w.y = cvtpk(a[2], a[3]); w.z = cvtpk(b[0], b[1]); w.w = cvtpk(b[2], b[3]); return w; }
;     __device__ __forceinline__ void operator()(const pg8::f32x4 (&acc)[2][2][4][2], const pg8::Unit& u, int wr, int wc, int fr, int fq) const {
;     ...
;             for (int m = 0; m < 4; ++m) {
;                 const int rloc = ai * 128 + wr * 64 + m * 16 + fr, row = u.pm * 256 + rloc;
;                 float mu = 0.f, rstd = 1.f; if (pst) ln_row_stats(pst, rloc, mu, rstd);
;                 float s = 0.f, q = 0.f;
; #pragma unroll
;                 for (int bj = 0; bj < 2; ++bj) {
;                     const int col = col0 + bj * 128;
;                     const u32x4 zw = zx[m][bj];
;                     f32x4 x0 = {bflo(zw.x), bfhi(zw.x), bflo(zw.y), bfhi(zw.y)}, x1 = {bflo(zw.z), bfhi(zw.z), bflo(zw.w), bfhi(zw.w)};
;                     if (pst) { const f32x4 g0 = *(const f32x4*)(pg + col), g1 = *(const f32x4*)(pg + col + 4), b0 = *(const f32x4*)(pb + col), b1 = *(const f32x4*)(pb + col + 4);
;                         x0 = (x0 - mu) * rstd * g0 + b0; x1 = (x1 - mu) * rstd * g1 + b1; }
;                     x0 = x0 * ALPHA + acc[ai][bj][m][0]; x1 = x1 * ALPHA + acc[ai][bj][m][1];
;                     if (Z) { float* p = Z + (size_t)row * 1024 + col; *(f32x4*)p = x0; *(f32x4*)(p + 4) = x1; }
;                     *(u32x4*)(ZB + (size_t)row * 1024 + col) = pack8(x0, x1);
.LBB0_1716:
	s_or_b64 exec, exec, s[0:1]
	ds_read_b64 v[82:83], v204 offset:384
	v_lshlrev_b32_e32 v106, 16, v102
	v_and_b32_e32 v107, 0xffff0000, v102
	v_lshlrev_b32_e32 v108, 16, v103
	v_and_b32_e32 v109, 0xffff0000, v103
	v_lshlrev_b32_e32 v110, 16, v104
	v_and_b32_e32 v111, 0xffff0000, v104
	v_lshlrev_b32_e32 v112, 16, v105
	v_and_b32_e32 v113, 0xffff0000, v105
	ds_read_b128 v[84:87], v80 offset:16
	s_waitcnt lgkmcnt(1)
	ds_read_b128 v[94:97], v80
	ds_read_b128 v[98:101], v80 offset:1040
	ds_read_b128 v[102:105], v80 offset:1024
	s_waitcnt lgkmcnt(0)
	v_sub_f32_e32 v107, v107, v82
	v_sub_f32_e32 v106, v106, v82
	v_sub_f32_e32 v109, v109, v82
	v_sub_f32_e32 v108, v108, v82
	v_pk_mul_f32 v[106:107], v[82:83], v[106:107] op_sel:[1,0]
	v_pk_mul_f32 v[108:109], v[82:83], v[108:109] op_sel:[1,0]
	v_lshlrev_b64 v[88:89], 12, v[178:179]
	s_and_b64 vcc, exec, s[40:41]
	s_nop 0
	v_pk_fma_f32 v[94:95], v[94:95], v[106:107], v[102:103]
	v_sub_f32_e32 v103, v111, v82
	v_sub_f32_e32 v102, v110, v82
	v_pk_fma_f32 v[96:97], v[96:97], v[108:109], v[104:105]
	v_sub_f32_e32 v105, v113, v82
	v_sub_f32_e32 v104, v112, v82
	v_pk_mul_f32 v[102:103], v[82:83], v[102:103] op_sel:[1,0]
	v_pk_mul_f32 v[104:105], v[82:83], v[104:105] op_sel:[1,0]
	v_pk_fma_f32 v[84:85], v[84:85], v[102:103], v[98:99]
	v_pk_fma_f32 v[86:87], v[86:87], v[104:105], v[100:101]
	v_pk_fma_f32 v[72:73], v[84:85], s[34:35], v[72:73] op_sel_hi:[1,0,1]
	v_lshl_add_u64 v[84:85], s[96:97], 0, v[88:89]
	v_pk_fma_f32 v[78:79], v[96:97], s[34:35], v[78:79] op_sel_hi:[1,0,1]
	v_pk_fma_f32 v[76:77], v[94:95], s[34:35], v[76:77] op_sel_hi:[1,0,1]
	v_pk_fma_f32 v[74:75], v[86:87], s[34:35], v[74:75] op_sel_hi:[1,0,1]
	v_lshl_add_u64 v[86:87], v[172:173], 2, v[84:85]
	s_cbranch_vccnz .LBB0_1718
	global_store_dwordx4 v[86:87], v[76:79], off
	global_store_dwordx4 v[86:87], v[72:75], off offset:16
.LBB0_1718:
	v_lshl_add_u64 v[84:85], s[20:21], 0, v[180:181]
	v_cvt_pk_bf16_f32 v94, v76, v77
	v_cvt_pk_bf16_f32 v95, v78, v79
	v_cvt_pk_bf16_f32 v96, v72, v73
	v_cvt_pk_bf16_f32 v97, v74, v75
	v_lshl_add_u64 v[84:85], v[172:173], 1, v[84:85]
	global_store_dwordx4 v[84:85], v[94:97], off
	v_lshlrev_b32_e32 v108, 16, v90
	v_and_b32_e32 v109, 0xffff0000, v90
	v_lshlrev_b32_e32 v106, 16, v91
	v_and_b32_e32 v107, 0xffff0000, v91
	v_lshlrev_b32_e32 v112, 16, v92
	v_and_b32_e32 v113, 0xffff0000, v92
	v_lshlrev_b32_e32 v114, 16, v93
	v_and_b32_e32 v115, 0xffff0000, v93
	ds_read_b128 v[88:91], v80 offset:528
	ds_read_b128 v[92:95], v80 offset:512
	ds_read_b128 v[96:99], v80 offset:1552
	ds_read_b128 v[100:103], v80 offset:1536
	v_mov_b32_e32 v104, v83
	v_mov_b32_e32 v105, v83
	v_sub_f32_e32 v109, v109, v82
	v_sub_f32_e32 v108, v108, v82
	v_pk_mul_f32 v[108:109], v[104:105], v[108:109]
	v_sub_f32_e32 v107, v107, v82
	v_sub_f32_e32 v106, v106, v82
	v_mov_b32_e32 v110, v83
	v_mov_b32_e32 v111, v83
	v_sub_f32_e32 v83, v113, v82
	v_pk_mul_f32 v[106:107], v[110:111], v[106:107]
	s_and_b64 vcc, exec, s[40:41]
	s_waitcnt lgkmcnt(0)
	v_pk_fma_f32 v[92:93], v[108:109], v[92:93], v[100:101]
	v_sub_f32_e32 v101, v115, v82
	v_sub_f32_e32 v100, v114, v82
	v_sub_f32_e32 v82, v112, v82
	v_pk_mul_f32 v[82:83], v[104:105], v[82:83]
	v_pk_mul_f32 v[100:101], v[110:111], v[100:101]
	v_pk_fma_f32 v[94:95], v[106:107], v[94:95], v[102:103]
	v_pk_fma_f32 v[90:91], v[100:101], v[90:91], v[98:99]
	v_pk_fma_f32 v[82:83], v[82:83], v[88:89], v[96:97]
	v_pk_fma_f32 v[68:69], v[92:93], s[34:35], v[68:69] op_sel_hi:[1,0,1]
	v_pk_fma_f32 v[70:71], v[94:95], s[34:35], v[70:71] op_sel_hi:[1,0,1]
	v_pk_fma_f32 v[64:65], v[82:83], s[34:35], v[64:65] op_sel_hi:[1,0,1]
	v_pk_fma_f32 v[66:67], v[90:91], s[34:35], v[66:67] op_sel_hi:[1,0,1]
	s_cbranch_vccnz .LBB0_1720
	global_store_dwordx4 v[86:87], v[68:71], off offset:512
	global_store_dwordx4 v[86:87], v[64:67], off offset:528

; __device__ __forceinline__ float bflo(unsigned w) { return __uint_as_float(w << 16); }
; __device__ __forceinline__ float bfhi(unsigned w) { return __uint_as_float(w & 0xffff0000u); }
; __device__ __forceinline__ u32x4 pack8(f32x4 a, f32x4 b) { u32x4 w; w.x = cvtpk(a[0], a[1]); w.y = cvtpk(a[2], a[3]); w.z = cvtpk(b[0], b[1]); w.w = cvtpk(b[2], b[3]); return w; }
;     __device__ __forceinline__ void operator()(const pg8::f32x4 (&acc)[2][2][4][2], const pg8::Unit& u, int wr, int wc, int fr, int fq) const {
;     ...
;             for (int m = 0; m < 4; ++m)
; #pragma unroll
;                 for (int bj = 0; bj < 2; ++bj) zx[m][bj] = *(const u32x4*)(ZB + (size_t)(u.pm * 256 + ai * 128 + wr * 64 + m * 16 + fr) * 1024 + col0 + bj * 128);
;             if (ai == 0) ln_table(pst, u.pm, key, wr, wc, fr, fq);
; #pragma unroll
;             for (int m = 0; m < 4; ++m) {
;                 const int rloc = ai * 128 + wr * 64 + m * 16 + fr, row = u.pm * 256 + rloc;
;                 float mu = 0.f, rstd = 1.f; if (pst) ln_row_stats(pst, rloc, mu, rstd);
;                 float s = 0.f, q = 0.f;
; #pragma unroll
;                 for (int bj = 0; bj < 2; ++bj) {
;                     const int col = col0 + bj * 128;
;                     const u32x4 zw = zx[m][bj];
;                     f32x4 x0 = {bflo(zw.x), bfhi(zw.x), bflo(zw.y), bfhi(zw.y)}, x1 = {bflo(zw.z), bfhi(zw.z), bflo(zw.w), bfhi(zw.w)};
;                     if (pst) { const f32x4 g0 = *(const f32x4*)(pg + col), g1 = *(const f32x4*)(pg + col + 4), b0 = *(const f32x4*)(pb + col), b1 = *(const f32x4*)(pb + col + 4);
;                         x0 = (x0 - mu) * rstd * g0 + b0; x1 = (x1 - mu) * rstd * g1 + b1; }
;                     x0 = x0 * ALPHA + acc[ai][bj][m][0]; x1 = x1 * ALPHA + acc[ai][bj][m][1];
;                     if (Z) { float* p = Z + (size_t)row * 1024 + col; *(f32x4*)p = x0; *(f32x4*)(p + 4) = x1; }
;                     *(u32x4*)(ZB + (size_t)row * 1024 + col) = pack8(x0, x1);
.LBB0_1722:
	s_or_b64 exec, exec, s[0:1]
	v_add_u32_e32 v106, 0x80, v176
	v_ashrrev_i32_e32 v107, 31, v106
	v_lshlrev_b64 v[110:111], 11, v[106:107]
	v_lshl_add_u64 v[64:65], v[174:175], 0, v[110:111]
	global_load_dwordx4 v[114:117], v[64:65], off
	global_load_dwordx4 v[90:93], v[64:65], off offset:256
	v_add_u32_e32 v102, 0x90, v176
	v_ashrrev_i32_e32 v103, 31, v102
	v_add_u32_e32 v98, 0xa0, v176
	v_lshlrev_b64 v[104:105], 11, v[102:103]
	v_ashrrev_i32_e32 v99, 31, v98
	v_add_u32_e32 v94, 0xb0, v176
	v_lshl_add_u64 v[64:65], v[174:175], 0, v[104:105]
	v_lshlrev_b64 v[100:101], 11, v[98:99]
	v_ashrrev_i32_e32 v95, 31, v94
	global_load_dwordx4 v[86:89], v[64:65], off
	global_load_dwordx4 v[82:85], v[64:65], off offset:256
	v_lshl_add_u64 v[64:65], v[174:175], 0, v[100:101]
	v_lshlrev_b64 v[96:97], 11, v[94:95]
	global_load_dwordx4 v[76:79], v[64:65], off
	s_waitcnt lgkmcnt(0)
	global_load_dwordx4 v[72:75], v[64:65], off offset:256
	v_lshl_add_u64 v[64:65], v[174:175], 0, v[96:97]
	global_load_dwordx4 v[68:71], v[64:65], off
	s_nop 0
	global_load_dwordx4 v[64:67], v[64:65], off offset:256
	ds_read_b64 v[108:109], v204 offset:1024
	v_lshlrev_b64 v[112:113], 12, v[106:107]
	v_lshl_add_u64 v[112:113], s[96:97], 0, v[112:113]
	s_and_b64 vcc, exec, s[40:41]
	v_lshl_add_u64 v[112:113], v[172:173], 2, v[112:113]
	s_waitcnt vmcnt(0)
	v_lshlrev_b32_e32 v130, 16, v114
	v_and_b32_e32 v131, 0xffff0000, v114
	v_lshlrev_b32_e32 v132, 16, v115
	v_and_b32_e32 v133, 0xffff0000, v115
	v_lshlrev_b32_e32 v134, 16, v116
	v_and_b32_e32 v135, 0xffff0000, v116
	v_lshlrev_b32_e32 v136, 16, v117
	v_and_b32_e32 v137, 0xffff0000, v117
	ds_read_b128 v[114:117], v80 offset:16
	ds_read_b128 v[118:121], v80
	ds_read_b128 v[122:125], v80 offset:1040
	ds_read_b128 v[126:129], v80 offset:1024
	s_waitcnt lgkmcnt(0)
	v_sub_f32_e32 v131, v131, v108
	v_sub_f32_e32 v130, v130, v108
	v_sub_f32_e32 v133, v133, v108
	v_sub_f32_e32 v132, v132, v108
	v_pk_mul_f32 v[132:133], v[108:109], v[132:133] op_sel:[1,0]
	v_pk_mul_f32 v[130:131], v[108:109], v[130:131] op_sel:[1,0]
	s_nop 0
	v_pk_fma_f32 v[120:121], v[120:121], v[132:133], v[128:129]
	v_pk_fma_f32 v[118:119], v[118:119], v[130:131], v[126:127]
	v_sub_f32_e32 v127, v135, v108
	v_sub_f32_e32 v126, v134, v108
	v_sub_f32_e32 v129, v137, v108
	v_sub_f32_e32 v128, v136, v108
	v_pk_mul_f32 v[128:129], v[108:109], v[128:129] op_sel:[1,0]
	v_pk_mul_f32 v[126:127], v[108:109], v[126:127] op_sel:[1,0]
	v_pk_fma_f32 v[116:117], v[116:117], v[128:129], v[124:125]
	v_pk_fma_f32 v[114:115], v[114:115], v[126:127], v[122:123]
	v_pk_fma_f32 v[62:63], v[120:121], s[34:35], v[62:63] op_sel_hi:[1,0,1]
	v_pk_fma_f32 v[60:61], v[118:119], s[34:35], v[60:61] op_sel_hi:[1,0,1]
	v_pk_fma_f32 v[58:59], v[116:117], s[34:35], v[58:59] op_sel_hi:[1,0,1]
	v_pk_fma_f32 v[56:57], v[114:115], s[34:35], v[56:57] op_sel_hi:[1,0,1]
	s_cbranch_vccnz .LBB0_1724
	global_store_dwordx4 v[112:113], v[60:63], off
	global_store_dwordx4 v[112:113], v[56:59], off offset:16
.LBB0_1724:
	v_lshl_add_u64 v[110:111], s[20:21], 0, v[110:111]
	v_cvt_pk_bf16_f32 v114, v60, v61
	v_cvt_pk_bf16_f32 v115, v62, v63
	v_cvt_pk_bf16_f32 v116, v56, v57
	v_cvt_pk_bf16_f32 v117, v58, v59
	v_lshl_add_u64 v[110:111], v[172:173], 1, v[110:111]
	global_store_dwordx4 v[110:111], v[114:117], off
	v_lshlrev_b32_e32 v130, 16, v90
	v_and_b32_e32 v131, 0xffff0000, v90
	v_lshlrev_b32_e32 v128, 16, v91
	v_and_b32_e32 v129, 0xffff0000, v91
	v_lshlrev_b32_e32 v134, 16, v92
	v_and_b32_e32 v135, 0xffff0000, v92
	v_lshlrev_b32_e32 v136, 16, v93
	v_and_b32_e32 v137, 0xffff0000, v93
	ds_read_b128 v[90:93], v80 offset:528
	ds_read_b128 v[114:117], v80 offset:512
	ds_read_b128 v[118:121], v80 offset:1552
	ds_read_b128 v[122:125], v80 offset:1536
	v_mov_b32_e32 v126, v109
	v_mov_b32_e32 v127, v109
	v_sub_f32_e32 v131, v131, v108
	v_sub_f32_e32 v130, v130, v108
	v_pk_mul_f32 v[130:131], v[126:127], v[130:131]
	v_sub_f32_e32 v129, v129, v108
	v_sub_f32_e32 v128, v128, v108
	v_mov_b32_e32 v132, v109
	v_mov_b32_e32 v133, v109
	v_sub_f32_e32 v109, v135, v108
	v_pk_mul_f32 v[128:129], v[132:133], v[128:129]
	s_and_b64 vcc, exec, s[40:41]
	s_waitcnt lgkmcnt(0)
	v_pk_fma_f32 v[114:115], v[130:131], v[114:115], v[122:123]
	v_sub_f32_e32 v123, v137, v108
	v_sub_f32_e32 v122, v136, v108
	v_sub_f32_e32 v108, v134, v108
	v_pk_mul_f32 v[108:109], v[126:127], v[108:109]
	v_pk_mul_f32 v[122:123], v[132:133], v[122:123]
	v_pk_fma_f32 v[116:117], v[128:129], v[116:117], v[124:125]
	v_pk_fma_f32 v[92:93], v[122:123], v[92:93], v[120:121]
	v_pk_fma_f32 v[90:91], v[108:109], v[90:91], v[118:119]
	v_pk_fma_f32 v[52:53], v[114:115], s[34:35], v[52:53] op_sel_hi:[1,0,1]
	v_pk_fma_f32 v[54:55], v[116:117], s[34:35], v[54:55] op_sel_hi:[1,0,1]
	v_pk_fma_f32 v[48:49], v[90:91], s[34:35], v[48:49] op_sel_hi:[1,0,1]
	v_pk_fma_f32 v[50:51], v[92:93], s[34:35], v[50:51] op_sel_hi:[1,0,1]
	s_cbranch_vccnz .LBB0_1726
	global_store_dwordx4 v[112:113], v[52:55], off offset:512
	global_store_dwordx4 v[112:113], v[48:51], off offset:528

; __device__ __forceinline__ float bflo(unsigned w) { return __uint_as_float(w << 16); }
; __device__ __forceinline__ float bfhi(unsigned w) { return __uint_as_float(w & 0xffff0000u); }
; __device__ __forceinline__ u32x4 pack8(f32x4 a, f32x4 b) { u32x4 w; w.x = cvtpk(a[0], a[1]); w.y = cvtpk(a[2], a[3]); w.z = cvtpk(b[0], b[1]); w.w = cvtpk(b[2], b[3]); return w; }
;     __device__ __forceinline__ void operator()(const pg8::f32x4 (&acc)[2][2][4][2], const pg8::Unit& u, int wr, int wc, int fr, int fq) const {
;     ...
;             for (int m = 0; m < 4; ++m) {
;                 const int rloc = ai * 128 + wr * 64 + m * 16 + fr, row = u.pm * 256 + rloc;
;                 float mu = 0.f, rstd = 1.f; if (pst) ln_row_stats(pst, rloc, mu, rstd);
;                 float s = 0.f, q = 0.f;
; #pragma unroll
;                 for (int bj = 0; bj < 2; ++bj) {
;                     const int col = col0 + bj * 128;
;                     const u32x4 zw = zx[m][bj];
;                     f32x4 x0 = {bflo(zw.x), bfhi(zw.x), bflo(zw.y), bfhi(zw.y)}, x1 = {bflo(zw.z), bfhi(zw.z), bflo(zw.w), bfhi(zw.w)};
;                     if (pst) { const f32x4 g0 = *(const f32x4*)(pg + col), g1 = *(const f32x4*)(pg + col + 4), b0 = *(const f32x4*)(pb + col), b1 = *(const f32x4*)(pb + col + 4);
;                         x0 = (x0 - mu) * rstd * g0 + b0; x1 = (x1 - mu) * rstd * g1 + b1; }
;                     x0 = x0 * ALPHA + acc[ai][bj][m][0]; x1 = x1 * ALPHA + acc[ai][bj][m][1];
;                     if (Z) { float* p = Z + (size_t)row * 1024 + col; *(f32x4*)p = x0; *(f32x4*)(p + 4) = x1; }
;                     *(u32x4*)(ZB + (size_t)row * 1024 + col) = pack8(x0, x1);
.LBB0_1728:
	s_or_b64 exec, exec, s[0:1]
	ds_read_b64 v[48:49], v204 offset:1152
	v_lshlrev_b32_e32 v90, 16, v86
	v_and_b32_e32 v91, 0xffff0000, v86
	v_lshlrev_b32_e32 v92, 16, v87
	v_and_b32_e32 v93, 0xffff0000, v87
	v_lshlrev_b32_e32 v106, 16, v88
	v_and_b32_e32 v107, 0xffff0000, v88
	v_lshlrev_b32_e32 v108, 16, v89
	v_and_b32_e32 v109, 0xffff0000, v89
	ds_read_b128 v[50:53], v80 offset:16
	s_waitcnt lgkmcnt(1)
	ds_read_b128 v[54:57], v80
	ds_read_b128 v[58:61], v80 offset:1040
	ds_read_b128 v[86:89], v80 offset:1024
	s_waitcnt lgkmcnt(0)
	v_sub_f32_e32 v91, v91, v48
	v_sub_f32_e32 v90, v90, v48
	v_sub_f32_e32 v93, v93, v48
	v_sub_f32_e32 v92, v92, v48
	v_pk_mul_f32 v[90:91], v[48:49], v[90:91] op_sel:[1,0]
	v_pk_mul_f32 v[92:93], v[48:49], v[92:93] op_sel:[1,0]
	v_lshlrev_b64 v[62:63], 12, v[102:103]
	s_and_b64 vcc, exec, s[40:41]
	s_nop 0
	v_pk_fma_f32 v[54:55], v[54:55], v[90:91], v[86:87]
	v_sub_f32_e32 v87, v107, v48
	v_sub_f32_e32 v86, v106, v48
	v_pk_fma_f32 v[56:57], v[56:57], v[92:93], v[88:89]
	v_sub_f32_e32 v89, v109, v48
	v_sub_f32_e32 v88, v108, v48
	v_pk_mul_f32 v[86:87], v[48:49], v[86:87] op_sel:[1,0]
	v_pk_mul_f32 v[88:89], v[48:49], v[88:89] op_sel:[1,0]
	v_pk_fma_f32 v[50:51], v[50:51], v[86:87], v[58:59]
	v_pk_fma_f32 v[52:53], v[52:53], v[88:89], v[60:61]
	v_pk_fma_f32 v[40:41], v[50:51], s[34:35], v[40:41] op_sel_hi:[1,0,1]
	v_lshl_add_u64 v[50:51], s[96:97], 0, v[62:63]
	v_pk_fma_f32 v[46:47], v[56:57], s[34:35], v[46:47] op_sel_hi:[1,0,1]
	v_pk_fma_f32 v[44:45], v[54:55], s[34:35], v[44:45] op_sel_hi:[1,0,1]
	v_pk_fma_f32 v[42:43], v[52:53], s[34:35], v[42:43] op_sel_hi:[1,0,1]
	v_lshl_add_u64 v[52:53], v[172:173], 2, v[50:51]
	s_cbranch_vccnz .LBB0_1730
	global_store_dwordx4 v[52:53], v[44:47], off
	global_store_dwordx4 v[52:53], v[40:43], off offset:16
.LBB0_1730:
	v_lshl_add_u64 v[50:51], s[20:21], 0, v[104:105]
	v_cvt_pk_bf16_f32 v54, v44, v45
	v_cvt_pk_bf16_f32 v55, v46, v47
	v_cvt_pk_bf16_f32 v56, v40, v41
	v_cvt_pk_bf16_f32 v57, v42, v43
	v_lshl_add_u64 v[50:51], v[172:173], 1, v[50:51]
	global_store_dwordx4 v[50:51], v[54:57], off
	v_lshlrev_b32_e32 v92, 16, v82
	v_and_b32_e32 v93, 0xffff0000, v82
	v_lshlrev_b32_e32 v90, 16, v83
	v_and_b32_e32 v91, 0xffff0000, v83
	v_lshlrev_b32_e32 v106, 16, v84
	v_and_b32_e32 v107, 0xffff0000, v84
	v_lshlrev_b32_e32 v108, 16, v85
	v_and_b32_e32 v109, 0xffff0000, v85
	ds_read_b128 v[54:57], v80 offset:528
	ds_read_b128 v[58:61], v80 offset:512
	ds_read_b128 v[82:85], v80 offset:1552
	ds_read_b128 v[86:89], v80 offset:1536
	v_mov_b32_e32 v62, v49
	v_mov_b32_e32 v63, v49
	v_sub_f32_e32 v93, v93, v48
	v_sub_f32_e32 v92, v92, v48
	v_pk_mul_f32 v[92:93], v[62:63], v[92:93]
	v_sub_f32_e32 v91, v91, v48
	v_sub_f32_e32 v90, v90, v48
	v_mov_b32_e32 v104, v49
	v_mov_b32_e32 v105, v49
	v_sub_f32_e32 v49, v107, v48
	v_pk_mul_f32 v[90:91], v[104:105], v[90:91]
	s_and_b64 vcc, exec, s[40:41]
	s_waitcnt lgkmcnt(0)
	v_pk_fma_f32 v[58:59], v[92:93], v[58:59], v[86:87]
	v_sub_f32_e32 v87, v109, v48
	v_sub_f32_e32 v86, v108, v48
	v_sub_f32_e32 v48, v106, v48
	v_pk_mul_f32 v[48:49], v[62:63], v[48:49]
	v_pk_mul_f32 v[62:63], v[104:105], v[86:87]
	v_pk_fma_f32 v[60:61], v[90:91], v[60:61], v[88:89]
	v_pk_fma_f32 v[56:57], v[62:63], v[56:57], v[84:85]
	v_pk_fma_f32 v[48:49], v[48:49], v[54:55], v[82:83]
	v_pk_fma_f32 v[36:37], v[58:59], s[34:35], v[36:37] op_sel_hi:[1,0,1]
	v_pk_fma_f32 v[38:39], v[60:61], s[34:35], v[38:39] op_sel_hi:[1,0,1]
	v_pk_fma_f32 v[32:33], v[48:49], s[34:35], v[32:33] op_sel_hi:[1,0,1]
	v_pk_fma_f32 v[34:35], v[56:57], s[34:35], v[34:35] op_sel_hi:[1,0,1]
	s_cbranch_vccnz .LBB0_1732
	global_store_dwordx4 v[52:53], v[36:39], off offset:512
	global_store_dwordx4 v[52:53], v[32:35], off offset:528

; __device__ __forceinline__ float bflo(unsigned w) { return __uint_as_float(w << 16); }
; __device__ __forceinline__ float bfhi(unsigned w) { return __uint_as_float(w & 0xffff0000u); }
; __device__ __forceinline__ u32x4 pack8(f32x4 a, f32x4 b) { u32x4 w; w.x = cvtpk(a[0], a[1]); w.y = cvtpk(a[2], a[3]); w.z = cvtpk(b[0], b[1]); w.w = cvtpk(b[2], b[3]); return w; }
;     __device__ __forceinline__ void operator()(const pg8::f32x4 (&acc)[2][2][4][2], const pg8::Unit& u, int wr, int wc, int fr, int fq) const {
;     ...
;             for (int m = 0; m < 4; ++m) {
;                 const int rloc = ai * 128 + wr * 64 + m * 16 + fr, row = u.pm * 256 + rloc;
;                 float mu = 0.f, rstd = 1.f; if (pst) ln_row_stats(pst, rloc, mu, rstd);
;                 float s = 0.f, q = 0.f;
; #pragma unroll
;                 for (int bj = 0; bj < 2; ++bj) {
;                     const int col = col0 + bj * 128;
;                     const u32x4 zw = zx[m][bj];
;                     f32x4 x0 = {bflo(zw.x), bfhi(zw.x), bflo(zw.y), bfhi(zw.y)}, x1 = {bflo(zw.z), bfhi(zw.z), bflo(zw.w), bfhi(zw.w)};
;                     if (pst) { const f32x4 g0 = *(const f32x4*)(pg + col), g1 = *(const f32x4*)(pg + col + 4), b0 = *(const f32x4*)(pb + col), b1 = *(const f32x4*)(pb + col + 4);
;                         x0 = (x0 - mu) * rstd * g0 + b0; x1 = (x1 - mu) * rstd * g1 + b1; }
;                     x0 = x0 * ALPHA + acc[ai][bj][m][0]; x1 = x1 * ALPHA + acc[ai][bj][m][1];
;                     if (Z) { float* p = Z + (size_t)row * 1024 + col; *(f32x4*)p = x0; *(f32x4*)(p + 4) = x1; }
;                     *(u32x4*)(ZB + (size_t)row * 1024 + col) = pack8(x0, x1);
.LBB0_1734:
	s_or_b64 exec, exec, s[0:1]
	ds_read_b64 v[32:33], v204 offset:1280
	ds_read_b128 v[34:37], v80 offset:16
	s_waitcnt lgkmcnt(1)
	ds_read_b128 v[38:41], v80
	ds_read_b128 v[42:45], v80 offset:1040
	ds_read_b128 v[46:49], v80 offset:1024
	v_lshlrev_b32_e32 v52, 16, v76
	v_and_b32_e32 v53, 0xffff0000, v76
	v_lshlrev_b32_e32 v54, 16, v77
	v_and_b32_e32 v55, 0xffff0000, v77
	s_waitcnt lgkmcnt(0)
	v_sub_f32_e32 v53, v53, v32
	v_sub_f32_e32 v52, v52, v32
	v_lshlrev_b32_e32 v56, 16, v78
	v_and_b32_e32 v57, 0xffff0000, v78
	v_sub_f32_e32 v55, v55, v32
	v_sub_f32_e32 v54, v54, v32
	v_pk_mul_f32 v[52:53], v[32:33], v[52:53] op_sel:[1,0]
	v_lshlrev_b32_e32 v58, 16, v79
	v_and_b32_e32 v59, 0xffff0000, v79
	v_pk_mul_f32 v[54:55], v[32:33], v[54:55] op_sel:[1,0]
	v_lshlrev_b64 v[50:51], 12, v[98:99]
	s_and_b64 vcc, exec, s[40:41]
	s_nop 0
	v_pk_fma_f32 v[38:39], v[38:39], v[52:53], v[46:47]
	v_sub_f32_e32 v47, v57, v32
	v_sub_f32_e32 v46, v56, v32
	v_pk_fma_f32 v[40:41], v[40:41], v[54:55], v[48:49]
	v_sub_f32_e32 v49, v59, v32
	v_sub_f32_e32 v48, v58, v32
	v_pk_mul_f32 v[46:47], v[32:33], v[46:47] op_sel:[1,0]
	v_pk_mul_f32 v[48:49], v[32:33], v[48:49] op_sel:[1,0]
	v_pk_fma_f32 v[34:35], v[34:35], v[46:47], v[42:43]
	v_pk_fma_f32 v[36:37], v[36:37], v[48:49], v[44:45]
	v_pk_fma_f32 v[24:25], v[34:35], s[34:35], v[24:25] op_sel_hi:[1,0,1]
	v_lshl_add_u64 v[34:35], s[96:97], 0, v[50:51]
	v_pk_fma_f32 v[30:31], v[40:41], s[34:35], v[30:31] op_sel_hi:[1,0,1]
	v_pk_fma_f32 v[28:29], v[38:39], s[34:35], v[28:29] op_sel_hi:[1,0,1]
	v_pk_fma_f32 v[26:27], v[36:37], s[34:35], v[26:27] op_sel_hi:[1,0,1]
	v_lshl_add_u64 v[36:37], v[172:173], 2, v[34:35]
	s_cbranch_vccnz .LBB0_1736
	global_store_dwordx4 v[36:37], v[28:31], off
	global_store_dwordx4 v[36:37], v[24:27], off offset:16
.LBB0_1736:
	v_lshl_add_u64 v[34:35], s[20:21], 0, v[100:101]
	v_cvt_pk_bf16_f32 v38, v28, v29
	v_cvt_pk_bf16_f32 v39, v30, v31
	v_cvt_pk_bf16_f32 v40, v24, v25
	v_cvt_pk_bf16_f32 v41, v26, v27
	v_lshl_add_u64 v[34:35], v[172:173], 1, v[34:35]
	global_store_dwordx4 v[34:35], v[38:41], off
	ds_read_b128 v[38:41], v80 offset:528
	s_nop 0
	ds_read_b128 v[42:45], v80 offset:512
	ds_read_b128 v[46:49], v80 offset:1552
	ds_read_b128 v[50:53], v80 offset:1536
	v_lshlrev_b32_e32 v58, 16, v72
	v_and_b32_e32 v59, 0xffff0000, v72
	v_mov_b32_e32 v54, v33
	v_mov_b32_e32 v55, v33
	v_sub_f32_e32 v59, v59, v32
	v_sub_f32_e32 v58, v58, v32
	v_lshlrev_b32_e32 v56, 16, v73
	v_and_b32_e32 v57, 0xffff0000, v73
	v_lshlrev_b32_e32 v62, 16, v74
	v_and_b32_e32 v63, 0xffff0000, v74
	v_lshlrev_b32_e32 v72, 16, v75
	v_and_b32_e32 v73, 0xffff0000, v75
	v_pk_mul_f32 v[58:59], v[54:55], v[58:59]
	v_sub_f32_e32 v57, v57, v32
	v_sub_f32_e32 v56, v56, v32
	v_mov_b32_e32 v60, v33
	v_mov_b32_e32 v61, v33
	v_sub_f32_e32 v33, v63, v32
	v_pk_mul_f32 v[56:57], v[60:61], v[56:57]
	s_and_b64 vcc, exec, s[40:41]
	s_waitcnt lgkmcnt(0)
	v_pk_fma_f32 v[42:43], v[58:59], v[42:43], v[50:51]
	v_sub_f32_e32 v51, v73, v32
	v_sub_f32_e32 v50, v72, v32
	v_sub_f32_e32 v32, v62, v32
	v_pk_mul_f32 v[32:33], v[54:55], v[32:33]
	v_pk_mul_f32 v[50:51], v[60:61], v[50:51]
	v_pk_fma_f32 v[44:45], v[56:57], v[44:45], v[52:53]
	v_pk_fma_f32 v[40:41], v[50:51], v[40:41], v[48:49]
	v_pk_fma_f32 v[32:33], v[32:33], v[38:39], v[46:47]
	v_pk_fma_f32 v[20:21], v[42:43], s[34:35], v[20:21] op_sel_hi:[1,0,1]
	v_pk_fma_f32 v[22:23], v[44:45], s[34:35], v[22:23] op_sel_hi:[1,0,1]
	v_pk_fma_f32 v[16:17], v[32:33], s[34:35], v[16:17] op_sel_hi:[1,0,1]
	v_pk_fma_f32 v[18:19], v[40:41], s[34:35], v[18:19] op_sel_hi:[1,0,1]
	s_cbranch_vccnz .LBB0_1738
	global_store_dwordx4 v[36:37], v[20:23], off offset:512
	global_store_dwordx4 v[36:37], v[16:19], off offset:528

; __device__ __forceinline__ float bflo(unsigned w) { return __uint_as_float(w << 16); }
; __device__ __forceinline__ float bfhi(unsigned w) { return __uint_as_float(w & 0xffff0000u); }
; __device__ __forceinline__ u32x4 pack8(f32x4 a, f32x4 b) { u32x4 w; w.x = cvtpk(a[0], a[1]); w.y = cvtpk(a[2], a[3]); w.z = cvtpk(b[0], b[1]); w.w = cvtpk(b[2], b[3]); return w; }
;     __device__ __forceinline__ void operator()(const pg8::f32x4 (&acc)[2][2][4][2], const pg8::Unit& u, int wr, int wc, int fr, int fq) const {
;     ...
;             for (int m = 0; m < 4; ++m) {
;                 const int rloc = ai * 128 + wr * 64 + m * 16 + fr, row = u.pm * 256 + rloc;
;                 float mu = 0.f, rstd = 1.f; if (pst) ln_row_stats(pst, rloc, mu, rstd);
;                 float s = 0.f, q = 0.f;
; #pragma unroll
;                 for (int bj = 0; bj < 2; ++bj) {
;                     const int col = col0 + bj * 128;
;                     const u32x4 zw = zx[m][bj];
;                     f32x4 x0 = {bflo(zw.x), bfhi(zw.x), bflo(zw.y), bfhi(zw.y)}, x1 = {bflo(zw.z), bfhi(zw.z), bflo(zw.w), bfhi(zw.w)};
;                     if (pst) { const f32x4 g0 = *(const f32x4*)(pg + col), g1 = *(const f32x4*)(pg + col + 4), b0 = *(const f32x4*)(pb + col), b1 = *(const f32x4*)(pb + col + 4);
;                         x0 = (x0 - mu) * rstd * g0 + b0; x1 = (x1 - mu) * rstd * g1 + b1; }
;                     x0 = x0 * ALPHA + acc[ai][bj][m][0]; x1 = x1 * ALPHA + acc[ai][bj][m][1];
;                     if (Z) { float* p = Z + (size_t)row * 1024 + col; *(f32x4*)p = x0; *(f32x4*)(p + 4) = x1; }
;                     *(u32x4*)(ZB + (size_t)row * 1024 + col) = pack8(x0, x1);
.LBB0_1740:
	s_or_b64 exec, exec, s[0:1]
	ds_read_b64 v[16:17], v204 offset:1408
	ds_read_b128 v[18:21], v80 offset:16
	s_waitcnt lgkmcnt(1)
	ds_read_b128 v[22:25], v80
	ds_read_b128 v[26:29], v80 offset:1040
	ds_read_b128 v[30:33], v80 offset:1024
	v_lshlrev_b32_e32 v36, 16, v68
	v_and_b32_e32 v37, 0xffff0000, v68
	v_lshlrev_b32_e32 v38, 16, v69
	v_and_b32_e32 v39, 0xffff0000, v69
	s_waitcnt lgkmcnt(0)
	v_sub_f32_e32 v37, v37, v16
	v_sub_f32_e32 v36, v36, v16
	v_lshlrev_b32_e32 v40, 16, v70
	v_and_b32_e32 v41, 0xffff0000, v70
	v_sub_f32_e32 v39, v39, v16
	v_sub_f32_e32 v38, v38, v16
	v_pk_mul_f32 v[36:37], v[16:17], v[36:37] op_sel:[1,0]
	v_lshlrev_b32_e32 v42, 16, v71
	v_and_b32_e32 v43, 0xffff0000, v71
	v_pk_mul_f32 v[38:39], v[16:17], v[38:39] op_sel:[1,0]
	v_lshlrev_b64 v[34:35], 12, v[94:95]
	s_and_b64 vcc, exec, s[40:41]
	s_nop 0
	v_pk_fma_f32 v[22:23], v[22:23], v[36:37], v[30:31]
	v_sub_f32_e32 v31, v41, v16
	v_sub_f32_e32 v30, v40, v16
	v_pk_fma_f32 v[24:25], v[24:25], v[38:39], v[32:33]
	v_sub_f32_e32 v33, v43, v16
	v_sub_f32_e32 v32, v42, v16
	v_pk_mul_f32 v[30:31], v[16:17], v[30:31] op_sel:[1,0]
	v_pk_mul_f32 v[32:33], v[16:17], v[32:33] op_sel:[1,0]
	v_pk_fma_f32 v[18:19], v[18:19], v[30:31], v[26:27]
	v_pk_fma_f32 v[20:21], v[20:21], v[32:33], v[28:29]
	v_pk_fma_f32 v[8:9], v[18:19], s[34:35], v[8:9] op_sel_hi:[1,0,1]
	v_lshl_add_u64 v[18:19], s[96:97], 0, v[34:35]
	v_pk_fma_f32 v[14:15], v[24:25], s[34:35], v[14:15] op_sel_hi:[1,0,1]
	v_pk_fma_f32 v[12:13], v[22:23], s[34:35], v[12:13] op_sel_hi:[1,0,1]
	v_pk_fma_f32 v[10:11], v[20:21], s[34:35], v[10:11] op_sel_hi:[1,0,1]
	v_lshl_add_u64 v[20:21], v[172:173], 2, v[18:19]
	s_cbranch_vccnz .LBB0_1742
	global_store_dwordx4 v[20:21], v[12:15], off
	global_store_dwordx4 v[20:21], v[8:11], off offset:16
.LBB0_1742:
	v_lshl_add_u64 v[18:19], s[20:21], 0, v[96:97]
	v_cvt_pk_bf16_f32 v22, v12, v13
	v_cvt_pk_bf16_f32 v23, v14, v15
	v_cvt_pk_bf16_f32 v24, v8, v9
	v_cvt_pk_bf16_f32 v25, v10, v11
	v_lshl_add_u64 v[18:19], v[172:173], 1, v[18:19]
	global_store_dwordx4 v[18:19], v[22:25], off
	ds_read_b128 v[22:25], v80 offset:528
	s_nop 0
	ds_read_b128 v[26:29], v80 offset:512
	ds_read_b128 v[30:33], v80 offset:1552
	ds_read_b128 v[34:37], v80 offset:1536
	v_lshlrev_b32_e32 v42, 16, v64
	v_and_b32_e32 v43, 0xffff0000, v64
	v_mov_b32_e32 v38, v17
	v_mov_b32_e32 v39, v17
	v_sub_f32_e32 v43, v43, v16
	v_sub_f32_e32 v42, v42, v16
	v_lshlrev_b32_e32 v40, 16, v65
	v_and_b32_e32 v41, 0xffff0000, v65
	v_lshlrev_b32_e32 v46, 16, v66
	v_and_b32_e32 v47, 0xffff0000, v66
	v_lshlrev_b32_e32 v48, 16, v67
	v_and_b32_e32 v49, 0xffff0000, v67
	v_pk_mul_f32 v[42:43], v[38:39], v[42:43]
	v_sub_f32_e32 v41, v41, v16
	v_sub_f32_e32 v40, v40, v16
	v_mov_b32_e32 v44, v17
	v_mov_b32_e32 v45, v17
	v_sub_f32_e32 v17, v47, v16
	v_pk_mul_f32 v[40:41], v[44:45], v[40:41]
	s_and_b64 vcc, exec, s[40:41]
	s_waitcnt lgkmcnt(0)
	v_pk_fma_f32 v[26:27], v[42:43], v[26:27], v[34:35]
	v_sub_f32_e32 v35, v49, v16
	v_sub_f32_e32 v34, v48, v16
	v_sub_f32_e32 v16, v46, v16
	v_pk_mul_f32 v[16:17], v[38:39], v[16:17]
	v_pk_mul_f32 v[34:35], v[44:45], v[34:35]
	v_pk_fma_f32 v[28:29], v[40:41], v[28:29], v[36:37]
	v_pk_fma_f32 v[24:25], v[34:35], v[24:25], v[32:33]
	v_pk_fma_f32 v[16:17], v[16:17], v[22:23], v[30:31]
	v_pk_fma_f32 v[4:5], v[26:27], s[34:35], v[4:5] op_sel_hi:[1,0,1]
	v_pk_fma_f32 v[6:7], v[28:29], s[34:35], v[6:7] op_sel_hi:[1,0,1]
	v_pk_fma_f32 v[0:1], v[16:17], s[34:35], v[0:1] op_sel_hi:[1,0,1]
	v_pk_fma_f32 v[2:3], v[24:25], s[34:35], v[2:3] op_sel_hi:[1,0,1]
	s_cbranch_vccnz .LBB0_1744
	global_store_dwordx4 v[20:21], v[4:7], off offset:512
	global_store_dwordx4 v[20:21], v[0:3], off offset:528
